# v11 + LN row statistics: ds_swizzle lane^16 exchange replaced by v_permlane16_swap (no LDS round trip)
# speedup vs baseline: 1.0036x; 1.0036x over previous
.LBB0_239:
	s_waitcnt lgkmcnt(0)
	v_readlane_b32 s2, v254, 27
	s_mul_i32 s2, s2, 0xb4000
	v_readlane_b32 s3, v254, 28
	s_add_u32 s2, s22, s2
	s_addc_u32 s3, s23, 0
	s_add_u32 s59, s2, 0x100000
	s_addc_u32 s67, s3, 0
	s_lshr_b32 s2, s72, 14
	s_add_i32 s18, s2, 8
	s_ashr_i32 s19, s53, 4
	s_and_b64 s[2:3], s[56:57], exec
	s_cselect_b32 s2, s18, s19
	s_mul_hi_i32 s3, s2, 0x4800
	s_mulk_i32 s2, 0x4800
	s_lshl_b32 s69, s82, 8
	s_lshl_b64 s[18:19], s[2:3], 2
	v_or_b32_e32 v132, s69, v177
	s_add_u32 s2, s59, s18
	s_addc_u32 s3, s67, s19
	v_ashrrev_i32_e32 v133, 31, v132
	v_lshl_add_u64 v[132:133], v[132:133], 2, s[2:3]
	s_mov_b64 s[2:3], 0x4000
	v_or_b32_e32 v148, v179, v178
	v_lshl_add_u64 v[144:145], v[132:133], 0, s[2:3]
	s_movk_i32 s2, 0x4000
	v_add_u32_e32 v148, s69, v148
	v_add_co_u32_e32 v140, vcc, s2, v132
	v_ashrrev_i32_e32 v149, 31, v148
	v_readlane_b32 s2, v254, 48
	v_lshl_add_u64 v[152:153], v[148:149], 2, s[14:15]
	v_readlane_b32 s3, v254, 49
	v_addc_co_u32_e32 v141, vcc, 0, v133, vcc
	v_lshl_add_u64 v[154:155], v[152:153], 0, s[28:29]
	v_lshl_add_u64 v[162:163], v[152:153], 0, s[2:3]
	v_readlane_b32 s2, v254, 52
	global_load_dwordx4 v[132:135], v[144:145], off offset:64
	global_load_dwordx4 v[136:139], v[144:145], off offset:512
	s_nop 0
	global_load_dwordx4 v[140:143], v[140:141], off
	s_nop 0
	global_load_dwordx4 v[144:147], v[144:145], off offset:576
	s_nop 0
	global_load_dwordx4 v[148:151], v[154:155], off nt
	s_nop 0
	global_load_dwordx4 v[154:157], v[154:155], off offset:512 nt
	s_nop 0
	global_load_dwordx4 v[158:161], v[162:163], off nt
	global_load_dwordx4 v[170:173], v[162:163], off offset:512 nt
	v_lshl_add_u64 v[162:163], v[152:153], 0, s[36:37]
	v_readlane_b32 s3, v254, 53
	global_load_dwordx4 v[186:189], v[162:163], off nt
	global_load_dwordx4 v[190:193], v[162:163], off offset:512 nt
	v_lshl_add_u64 v[162:163], v[152:153], 0, s[2:3]
	v_readlane_b32 s2, v254, 56
	global_load_dwordx4 v[194:197], v[162:163], off nt
	global_load_dwordx4 v[198:201], v[162:163], off offset:512 nt
	v_lshl_add_u64 v[162:163], v[152:153], 0, s[42:43]
	v_readlane_b32 s3, v254, 57
	global_load_dwordx4 v[202:205], v[162:163], off nt
	global_load_dwordx4 v[214:217], v[162:163], off offset:512 nt
	v_lshl_add_u64 v[162:163], v[152:153], 0, s[2:3]
	v_readlane_b32 s2, v254, 60
	global_load_dwordx4 v[218:221], v[162:163], off nt
	global_load_dwordx4 v[222:225], v[162:163], off offset:512 nt
	v_lshl_add_u64 v[162:163], v[152:153], 0, s[48:49]
	v_readlane_b32 s3, v254, 61
	global_load_dwordx4 v[226:229], v[162:163], off nt
	global_load_dwordx4 v[230:233], v[162:163], off offset:512 nt
	v_lshl_add_u64 v[162:163], v[152:153], 0, s[2:3]
	global_load_dwordx4 v[234:237], v[162:163], off nt
	global_load_dwordx4 v[238:241], v[162:163], off offset:512 nt
	s_waitcnt vmcnt(0)
	ds_write_b128 v176, v[148:151]
	ds_write_b128 v176, v[158:161] offset:1152
	ds_read_b128 v[148:151], v175
	ds_read_b128 v[158:161], v175 offset:64
	ds_write_b128 v176, v[154:157]
	ds_write_b128 v176, v[170:173] offset:1152
	ds_read_b128 v[154:157], v175
	ds_read_b128 v[170:173], v175 offset:64
	v_pk_add_f32 v[142:143], v[142:143], 1.0 op_sel_hi:[1,0]
	v_pk_add_f32 v[162:163], v[140:141], 1.0 op_sel_hi:[1,0]
	ds_write_b128 v176, v[186:189]
	ds_write_b128 v176, v[194:197] offset:1152
	v_pk_mul_f32 v[140:141], v[142:143], 0.5 op_sel_hi:[1,0]
	v_pk_mul_f32 v[142:143], v[162:163], 0.5 op_sel_hi:[1,0]
	s_waitcnt lgkmcnt(6)
	v_pk_mul_f32 v[162:163], v[160:161], s[80:81] op_sel_hi:[1,0]
	v_pk_mul_f32 v[206:207], v[158:159], s[80:81] op_sel_hi:[1,0]
	ds_read_b128 v[158:161], v175
	ds_read_b128 v[186:189], v175 offset:64
	v_pk_mul_f32 v[150:151], v[150:151], s[80:81] op_sel_hi:[1,0]
	v_pk_mul_f32 v[148:149], v[148:149], s[80:81] op_sel_hi:[1,0]
	v_pk_add_f32 v[134:135], v[134:135], 1.0 op_sel_hi:[1,0]
	v_pk_add_f32 v[132:133], v[132:133], 1.0 op_sel_hi:[1,0]
	v_pk_fma_f32 v[130:131], v[130:131], v[140:141], v[150:151]
	v_pk_fma_f32 v[128:129], v[128:129], v[142:143], v[148:149]
	v_pk_mul_f32 v[148:149], v[134:135], 0.5 op_sel_hi:[1,0]
	v_pk_mul_f32 v[150:151], v[132:133], 0.5 op_sel_hi:[1,0]
	v_pk_fma_f32 v[134:135], v[126:127], v[148:149], v[162:163]
	v_pk_fma_f32 v[132:133], v[124:125], v[150:151], v[206:207]
	v_pk_add_f32 v[124:125], v[138:139], 1.0 op_sel_hi:[1,0]
	v_pk_add_f32 v[126:127], v[136:137], 1.0 op_sel_hi:[1,0]
	s_waitcnt lgkmcnt(5)
	v_pk_mul_f32 v[156:157], v[156:157], s[80:81] op_sel_hi:[1,0]
	v_pk_mul_f32 v[154:155], v[154:155], s[80:81] op_sel_hi:[1,0]
	v_pk_mul_f32 v[124:125], v[124:125], 0.5 op_sel_hi:[1,0]
	v_pk_mul_f32 v[126:127], v[126:127], 0.5 op_sel_hi:[1,0]
	ds_write_b128 v176, v[190:193]
	ds_write_b128 v176, v[198:201] offset:1152
	v_pk_fma_f32 v[138:139], v[122:123], v[124:125], v[156:157]
	v_pk_fma_f32 v[136:137], v[120:121], v[126:127], v[154:155]
	s_waitcnt lgkmcnt(6)
	v_pk_mul_f32 v[162:163], v[172:173], s[80:81] op_sel_hi:[1,0]
	v_pk_mul_f32 v[194:195], v[170:171], s[80:81] op_sel_hi:[1,0]
	ds_read_b128 v[154:157], v175
	ds_read_b128 v[170:173], v175 offset:64
	v_pk_add_f32 v[120:121], v[146:147], 1.0 op_sel_hi:[1,0]
	v_pk_add_f32 v[122:123], v[144:145], 1.0 op_sel_hi:[1,0]
	v_pk_mul_f32 v[120:121], v[120:121], 0.5 op_sel_hi:[1,0]
	v_pk_mul_f32 v[122:123], v[122:123], 0.5 op_sel_hi:[1,0]
	v_pk_fma_f32 v[146:147], v[106:107], v[120:121], v[162:163]
	v_pk_fma_f32 v[144:145], v[104:105], v[122:123], v[194:195]
	s_waitcnt lgkmcnt(5)
	v_pk_mul_f32 v[104:105], v[160:161], s[80:81] op_sel_hi:[1,0]
	v_pk_mul_f32 v[106:107], v[158:159], s[80:81] op_sel_hi:[1,0]
	v_pk_fma_f32 v[110:111], v[110:111], v[140:141], v[104:105]
	v_pk_fma_f32 v[108:109], v[108:109], v[142:143], v[106:107]
	s_waitcnt lgkmcnt(4)
	v_pk_mul_f32 v[104:105], v[188:189], s[80:81] op_sel_hi:[1,0]
	v_pk_mul_f32 v[106:107], v[186:187], s[80:81] op_sel_hi:[1,0]
	v_pk_fma_f32 v[118:119], v[118:119], v[148:149], v[104:105]
	v_pk_fma_f32 v[116:117], v[116:117], v[150:151], v[106:107]
	s_waitcnt lgkmcnt(1)
	v_pk_mul_f32 v[104:105], v[156:157], s[80:81] op_sel_hi:[1,0]
	v_pk_mul_f32 v[106:107], v[154:155], s[80:81] op_sel_hi:[1,0]
	v_pk_fma_f32 v[102:103], v[102:103], v[124:125], v[104:105]
	s_waitcnt lgkmcnt(0)
	v_pk_mul_f32 v[104:105], v[172:173], s[80:81] op_sel_hi:[1,0]
	v_pk_mul_f32 v[154:155], v[170:171], s[80:81] op_sel_hi:[1,0]
	v_pk_fma_f32 v[100:101], v[100:101], v[126:127], v[106:107]
	v_pk_fma_f32 v[106:107], v[98:99], v[120:121], v[104:105]
	v_pk_fma_f32 v[104:105], v[96:97], v[122:123], v[154:155]
	v_readlane_b32 s2, v255, 0
	v_lshl_add_u64 v[96:97], v[152:153], 0, s[54:55]
	v_readlane_b32 s3, v255, 1
	global_load_dwordx4 v[154:157], v[96:97], off nt
	global_load_dwordx4 v[158:161], v[96:97], off offset:512 nt
	v_lshl_add_u64 v[96:97], v[152:153], 0, s[2:3]
	v_readlane_b32 s2, v255, 2
	global_load_dwordx4 v[170:173], v[96:97], off nt
	global_load_dwordx4 v[186:189], v[96:97], off offset:512 nt
	v_lshl_add_u64 v[96:97], v[152:153], 0, s[60:61]
	v_readlane_b32 s3, v255, 3
	global_load_dwordx4 v[190:193], v[96:97], off nt
	global_load_dwordx4 v[194:197], v[96:97], off offset:512 nt
	v_lshl_add_u64 v[96:97], v[152:153], 0, s[2:3]
	global_load_dwordx4 v[198:201], v[96:97], off nt
	global_load_dwordx4 v[250:253], v[96:97], off offset:512 nt
	ds_write_b128 v176, v[202:205]
	ds_write_b128 v176, v[218:221] offset:1152
	ds_read_b128 v[96:99], v175
	ds_read_b128 v[202:205], v175 offset:64
	ds_write_b128 v176, v[214:217]
	ds_write_b128 v176, v[222:225] offset:1152
	ds_read_b128 v[214:217], v175
	ds_read_b128 v[218:221], v175 offset:64
	ds_write_b128 v176, v[226:229]
	ds_write_b128 v176, v[234:237] offset:1152
	ds_read_b128 v[222:225], v175
	ds_read_b128 v[226:229], v175 offset:64
	s_waitcnt lgkmcnt(9)
	v_pk_mul_f32 v[96:97], v[96:97], s[80:81] op_sel_hi:[1,0]
	v_pk_mul_f32 v[98:99], v[98:99], s[80:81] op_sel_hi:[1,0]
	v_pk_fma_f32 v[92:93], v[92:93], v[142:143], v[96:97]
	s_waitcnt lgkmcnt(8)
	v_pk_mul_f32 v[96:97], v[204:205], s[80:81] op_sel_hi:[1,0]
	v_pk_mul_f32 v[162:163], v[202:203], s[80:81] op_sel_hi:[1,0]
	v_pk_fma_f32 v[94:95], v[94:95], v[140:141], v[98:99]
	v_pk_fma_f32 v[98:99], v[90:91], v[148:149], v[96:97]
	v_pk_fma_f32 v[96:97], v[88:89], v[150:151], v[162:163]
	ds_write_b128 v176, v[230:233]
	ds_write_b128 v176, v[238:241] offset:1152
	s_waitcnt lgkmcnt(7)
	v_pk_mul_f32 v[88:89], v[216:217], s[80:81] op_sel_hi:[1,0]
	v_pk_mul_f32 v[90:91], v[214:215], s[80:81] op_sel_hi:[1,0]
	ds_read_b128 v[202:205], v175
	ds_read_b128 v[214:217], v175 offset:64
	v_pk_fma_f32 v[86:87], v[86:87], v[124:125], v[88:89]
	s_waitcnt lgkmcnt(8)
	v_pk_mul_f32 v[88:89], v[220:221], s[80:81] op_sel_hi:[1,0]
	v_pk_mul_f32 v[162:163], v[218:219], s[80:81] op_sel_hi:[1,0]
	v_pk_fma_f32 v[84:85], v[84:85], v[126:127], v[90:91]
	v_pk_fma_f32 v[90:91], v[74:75], v[120:121], v[88:89]
	v_pk_fma_f32 v[88:89], v[72:73], v[122:123], v[162:163]
	s_waitcnt lgkmcnt(5)
	v_pk_mul_f32 v[72:73], v[224:225], s[80:81] op_sel_hi:[1,0]
	v_pk_mul_f32 v[74:75], v[222:223], s[80:81] op_sel_hi:[1,0]
	v_pk_fma_f32 v[78:79], v[78:79], v[140:141], v[72:73]
	v_pk_fma_f32 v[76:77], v[76:77], v[142:143], v[74:75]
	s_waitcnt lgkmcnt(4)
	v_pk_mul_f32 v[72:73], v[228:229], s[80:81] op_sel_hi:[1,0]
	v_pk_mul_f32 v[74:75], v[226:227], s[80:81] op_sel_hi:[1,0]
	v_pk_fma_f32 v[82:83], v[82:83], v[148:149], v[72:73]
	v_pk_fma_f32 v[80:81], v[80:81], v[150:151], v[74:75]
	s_waitcnt lgkmcnt(1)
	v_pk_mul_f32 v[72:73], v[204:205], s[80:81] op_sel_hi:[1,0]
	v_pk_mul_f32 v[74:75], v[202:203], s[80:81] op_sel_hi:[1,0]
	v_pk_fma_f32 v[70:71], v[70:71], v[124:125], v[72:73]
	s_waitcnt lgkmcnt(0)
	v_pk_mul_f32 v[72:73], v[216:217], s[80:81] op_sel_hi:[1,0]
	v_pk_mul_f32 v[162:163], v[214:215], s[80:81] op_sel_hi:[1,0]
	v_pk_fma_f32 v[68:69], v[68:69], v[126:127], v[74:75]
	v_pk_fma_f32 v[74:75], v[66:67], v[120:121], v[72:73]
	v_pk_fma_f32 v[72:73], v[64:65], v[122:123], v[162:163]
	v_readlane_b32 s2, v255, 4
	v_lshl_add_u64 v[64:65], v[152:153], 0, s[70:71]
	v_readlane_b32 s3, v255, 5
	global_load_dwordx4 v[202:205], v[64:65], off nt
	global_load_dwordx4 v[214:217], v[64:65], off offset:512 nt
	v_lshl_add_u64 v[64:65], v[152:153], 0, s[2:3]
	v_readlane_b32 s2, v255, 6
	global_load_dwordx4 v[218:221], v[64:65], off nt
	global_load_dwordx4 v[222:225], v[64:65], off offset:512 nt
	v_lshl_add_u64 v[64:65], v[152:153], 0, s[96:97]
	v_readlane_b32 s3, v255, 7
	global_load_dwordx4 v[226:229], v[64:65], off nt
	global_load_dwordx4 v[230:233], v[64:65], off offset:512 nt
	v_lshl_add_u64 v[64:65], v[152:153], 0, s[2:3]
	global_load_dwordx4 v[234:237], v[64:65], off nt
	global_load_dwordx4 v[238:241], v[64:65], off offset:512 nt
	s_waitcnt vmcnt(15)
	ds_write_b128 v176, v[154:157]
	s_waitcnt vmcnt(13)
	ds_write_b128 v176, v[170:173] offset:1152
	ds_read_b128 v[64:67], v175
	ds_read_b128 v[152:155], v175 offset:64
	ds_write_b128 v176, v[158:161]
	s_waitcnt vmcnt(12)
	ds_write_b128 v176, v[186:189] offset:1152
	ds_read_b128 v[156:159], v175
	ds_read_b128 v[160:163], v175 offset:64
	s_waitcnt vmcnt(11)
	ds_write_b128 v176, v[190:193]
	s_waitcnt vmcnt(9)
	ds_write_b128 v176, v[198:201] offset:1152
	ds_read_b128 v[170:173], v175
	ds_read_b128 v[186:189], v175 offset:64
	s_waitcnt lgkmcnt(9)
	v_pk_mul_f32 v[64:65], v[64:65], s[80:81] op_sel_hi:[1,0]
	v_pk_mul_f32 v[66:67], v[66:67], s[80:81] op_sel_hi:[1,0]
	v_pk_fma_f32 v[60:61], v[60:61], v[142:143], v[64:65]
	s_waitcnt lgkmcnt(8)
	v_pk_mul_f32 v[64:65], v[154:155], s[80:81] op_sel_hi:[1,0]
	v_pk_mul_f32 v[152:153], v[152:153], s[80:81] op_sel_hi:[1,0]
	v_pk_fma_f32 v[62:63], v[62:63], v[140:141], v[66:67]
	v_pk_fma_f32 v[66:67], v[58:59], v[148:149], v[64:65]
	v_pk_fma_f32 v[64:65], v[56:57], v[150:151], v[152:153]
	ds_write_b128 v176, v[194:197]
	s_waitcnt vmcnt(8)
	ds_write_b128 v176, v[250:253] offset:1152
	s_waitcnt lgkmcnt(7)
	v_pk_mul_f32 v[56:57], v[158:159], s[80:81] op_sel_hi:[1,0]
	v_pk_mul_f32 v[58:59], v[156:157], s[80:81] op_sel_hi:[1,0]
	ds_read_b128 v[152:155], v175
	ds_read_b128 v[156:159], v175 offset:64
	v_pk_fma_f32 v[54:55], v[54:55], v[124:125], v[56:57]
	s_waitcnt lgkmcnt(8)
	v_pk_mul_f32 v[56:57], v[162:163], s[80:81] op_sel_hi:[1,0]
	v_pk_mul_f32 v[160:161], v[160:161], s[80:81] op_sel_hi:[1,0]
	v_pk_fma_f32 v[52:53], v[52:53], v[126:127], v[58:59]
	v_pk_fma_f32 v[58:59], v[42:43], v[120:121], v[56:57]
	v_pk_fma_f32 v[56:57], v[40:41], v[122:123], v[160:161]
	s_waitcnt lgkmcnt(5)
	v_pk_mul_f32 v[40:41], v[172:173], s[80:81] op_sel_hi:[1,0]
	v_pk_mul_f32 v[42:43], v[170:171], s[80:81] op_sel_hi:[1,0]
	v_pk_fma_f32 v[46:47], v[46:47], v[140:141], v[40:41]
	v_pk_fma_f32 v[44:45], v[44:45], v[142:143], v[42:43]
	s_waitcnt lgkmcnt(4)
	v_pk_mul_f32 v[40:41], v[188:189], s[80:81] op_sel_hi:[1,0]
	v_pk_mul_f32 v[42:43], v[186:187], s[80:81] op_sel_hi:[1,0]
	v_pk_fma_f32 v[50:51], v[50:51], v[148:149], v[40:41]
	v_pk_fma_f32 v[48:49], v[48:49], v[150:151], v[42:43]
	s_waitcnt lgkmcnt(1)
	v_pk_mul_f32 v[40:41], v[154:155], s[80:81] op_sel_hi:[1,0]
	v_pk_mul_f32 v[42:43], v[152:153], s[80:81] op_sel_hi:[1,0]
	v_pk_fma_f32 v[38:39], v[38:39], v[124:125], v[40:41]
	s_waitcnt lgkmcnt(0)
	v_pk_mul_f32 v[40:41], v[158:159], s[80:81] op_sel_hi:[1,0]
	v_pk_mul_f32 v[152:153], v[156:157], s[80:81] op_sel_hi:[1,0]
	v_pk_fma_f32 v[36:37], v[36:37], v[126:127], v[42:43]
	v_pk_fma_f32 v[42:43], v[34:35], v[120:121], v[40:41]
	v_pk_fma_f32 v[40:41], v[32:33], v[122:123], v[152:153]
	s_nop 0
	s_waitcnt vmcnt(7)
	ds_write_b128 v176, v[202:205]
	s_waitcnt vmcnt(5)
	ds_write_b128 v176, v[218:221] offset:1152
	ds_read_b128 v[32:35], v175
	ds_read_b128 v[152:155], v175 offset:64
	ds_write_b128 v176, v[214:217]
	s_waitcnt vmcnt(4)
	ds_write_b128 v176, v[222:225] offset:1152
	ds_read_b128 v[156:159], v175
	ds_read_b128 v[160:163], v175 offset:64
	s_waitcnt vmcnt(3)
	ds_write_b128 v176, v[226:229]
	s_waitcnt vmcnt(1)
	ds_write_b128 v176, v[234:237] offset:1152
	ds_read_b128 v[170:173], v175
	ds_read_b128 v[186:189], v175 offset:64
	s_waitcnt lgkmcnt(9)
	v_pk_mul_f32 v[32:33], v[32:33], s[80:81] op_sel_hi:[1,0]
	v_pk_mul_f32 v[34:35], v[34:35], s[80:81] op_sel_hi:[1,0]
	v_pk_fma_f32 v[28:29], v[28:29], v[142:143], v[32:33]
	s_waitcnt lgkmcnt(8)
	v_pk_mul_f32 v[32:33], v[154:155], s[80:81] op_sel_hi:[1,0]
	v_pk_mul_f32 v[152:153], v[152:153], s[80:81] op_sel_hi:[1,0]
	v_pk_fma_f32 v[30:31], v[30:31], v[140:141], v[34:35]
	v_pk_fma_f32 v[34:35], v[26:27], v[148:149], v[32:33]
	v_pk_fma_f32 v[32:33], v[24:25], v[150:151], v[152:153]
	ds_write_b128 v176, v[230:233]
	s_waitcnt vmcnt(0)
	ds_write_b128 v176, v[238:241] offset:1152
	s_waitcnt lgkmcnt(7)
	v_pk_mul_f32 v[24:25], v[158:159], s[80:81] op_sel_hi:[1,0]
	v_pk_mul_f32 v[26:27], v[156:157], s[80:81] op_sel_hi:[1,0]
	ds_read_b128 v[152:155], v175
	ds_read_b128 v[156:159], v175 offset:64
	v_pk_fma_f32 v[22:23], v[22:23], v[124:125], v[24:25]
	s_waitcnt lgkmcnt(8)
	v_pk_mul_f32 v[24:25], v[162:163], s[80:81] op_sel_hi:[1,0]
	v_pk_mul_f32 v[160:161], v[160:161], s[80:81] op_sel_hi:[1,0]
	v_pk_fma_f32 v[20:21], v[20:21], v[126:127], v[26:27]
	v_pk_fma_f32 v[26:27], v[14:15], v[120:121], v[24:25]
	v_pk_fma_f32 v[24:25], v[12:13], v[122:123], v[160:161]
	s_waitcnt lgkmcnt(5)
	v_pk_mul_f32 v[12:13], v[172:173], s[80:81] op_sel_hi:[1,0]
	v_pk_mul_f32 v[160:161], v[170:171], s[80:81] op_sel_hi:[1,0]
	v_pk_fma_f32 v[14:15], v[114:115], v[140:141], v[12:13]
	v_pk_fma_f32 v[12:13], v[112:113], v[142:143], v[160:161]
	s_waitcnt lgkmcnt(4)
	v_pk_mul_f32 v[112:113], v[188:189], s[80:81] op_sel_hi:[1,0]
	v_pk_mul_f32 v[114:115], v[186:187], s[80:81] op_sel_hi:[1,0]
	v_pk_fma_f32 v[18:19], v[18:19], v[148:149], v[112:113]
	v_pk_fma_f32 v[16:17], v[16:17], v[150:151], v[114:115]
	s_waitcnt lgkmcnt(1)
	v_pk_mul_f32 v[112:113], v[154:155], s[80:81] op_sel_hi:[1,0]
	v_pk_mul_f32 v[114:115], v[152:153], s[80:81] op_sel_hi:[1,0]
	v_pk_fma_f32 v[6:7], v[6:7], v[124:125], v[112:113]
	s_waitcnt lgkmcnt(0)
	v_pk_mul_f32 v[112:113], v[158:159], s[80:81] op_sel_hi:[1,0]
	v_pk_fma_f32 v[4:5], v[4:5], v[126:127], v[114:115]
	v_pk_mul_f32 v[114:115], v[156:157], s[80:81] op_sel_hi:[1,0]
	v_pk_fma_f32 v[10:11], v[10:11], v[120:121], v[112:113]
	v_add_f32_e32 v112, v128, v129
	v_add_f32_e32 v113, v130, v131
	v_pk_fma_f32 v[8:9], v[8:9], v[122:123], v[114:115]
	v_add_f32_e32 v112, v112, v113
	v_mul_f32_e32 v113, v129, v129
	v_mul_f32_e32 v114, v131, v131
	v_fmac_f32_e32 v113, v128, v128
	v_fmac_f32_e32 v114, v130, v130
	v_add_f32_e32 v113, v113, v114
	v_add_f32_e32 v114, v132, v133
	v_add_f32_e32 v115, v134, v135
	v_add_f32_e32 v112, 0, v112
	v_add_f32_e32 v114, v114, v115
	v_add_f32_e32 v112, v114, v112
	v_mul_f32_e32 v114, v133, v133
	v_mul_f32_e32 v115, v135, v135
	v_fmac_f32_e32 v114, v132, v132
	v_fmac_f32_e32 v115, v134, v134
	v_add_f32_e32 v114, v114, v115
	v_add_f32_e32 v113, v113, v114
	v_add_f32_e32 v114, v136, v137
	v_add_f32_e32 v115, v138, v139
	v_add_f32_e32 v114, v114, v115
	v_add_f32_e32 v112, v114, v112
	v_mul_f32_e32 v114, v137, v137
	v_mul_f32_e32 v115, v139, v139
	v_fmac_f32_e32 v114, v136, v136
	v_fmac_f32_e32 v115, v138, v138
	v_add_f32_e32 v114, v114, v115
	v_add_f32_e32 v113, v114, v113
	v_add_f32_e32 v114, v144, v145
	v_add_f32_e32 v115, v146, v147
	v_add_f32_e32 v114, v114, v115
	v_add_f32_e32 v112, v114, v112
	v_mul_f32_e32 v114, v145, v145
	v_mul_f32_e32 v115, v147, v147
	v_fmac_f32_e32 v114, v144, v144
	v_fmac_f32_e32 v115, v146, v146
	v_add_f32_e32 v114, v114, v115
	v_add_f32_e32 v113, v114, v113
	ds_swizzle_b32 v114, v112 offset:swizzle(SWAP,16)
	ds_swizzle_b32 v115, v113 offset:swizzle(SWAP,16)
	s_waitcnt lgkmcnt(1)
	v_add_f32_e32 v112, v112, v114
	s_waitcnt lgkmcnt(0)
	v_add_f32_e32 v113, v113, v115
	v_mov_b32_e32 v114, v112
	v_mov_b32_e32 v115, v113
	s_nop 0
	v_permlane32_swap_b32_e32 v112, v114
	v_permlane32_swap_b32_e32 v113, v115
	s_and_saveexec_b64 s[2:3], s[8:9]
	v_pk_add_f32 v[112:113], v[112:113], v[114:115]
	ds_write_b64 v184, v[112:113]
	s_or_b64 exec, exec, s[2:3]
	v_add_f32_e32 v112, v108, v109
	v_add_f32_e32 v113, v110, v111
	v_add_f32_e32 v112, v112, v113
	v_mul_f32_e32 v113, v109, v109
	v_mul_f32_e32 v114, v111, v111
	v_fmac_f32_e32 v113, v108, v108
	v_fmac_f32_e32 v114, v110, v110
	v_add_f32_e32 v113, v113, v114
	v_add_f32_e32 v114, v116, v117
	v_add_f32_e32 v115, v118, v119
	v_add_f32_e32 v112, 0, v112
	v_add_f32_e32 v114, v114, v115
	v_add_f32_e32 v112, v114, v112
	v_mul_f32_e32 v114, v117, v117
	v_mul_f32_e32 v115, v119, v119
	v_fmac_f32_e32 v114, v116, v116
	v_fmac_f32_e32 v115, v118, v118
	v_add_f32_e32 v114, v114, v115
	v_add_f32_e32 v113, v113, v114
	v_add_f32_e32 v114, v100, v101
	v_add_f32_e32 v115, v102, v103
	v_add_f32_e32 v114, v114, v115
	v_add_f32_e32 v112, v114, v112
	v_mul_f32_e32 v114, v101, v101
	v_mul_f32_e32 v115, v103, v103
	v_fmac_f32_e32 v114, v100, v100
	v_fmac_f32_e32 v115, v102, v102
	v_add_f32_e32 v114, v114, v115
	v_add_f32_e32 v113, v114, v113
	v_add_f32_e32 v114, v104, v105
	v_add_f32_e32 v115, v106, v107
	v_add_f32_e32 v114, v114, v115
	v_add_f32_e32 v112, v114, v112
	v_mul_f32_e32 v114, v105, v105
	v_mul_f32_e32 v115, v107, v107
	v_fmac_f32_e32 v114, v104, v104
	v_fmac_f32_e32 v115, v106, v106
	v_add_f32_e32 v114, v114, v115
	v_add_f32_e32 v113, v114, v113
	v_mov_b32_e32 v114, v112
	v_mov_b32_e32 v115, v113
	s_nop 0
	v_permlane16_swap_b32_e32 v112, v114
	v_permlane16_swap_b32_e32 v113, v115
	v_add_f32_e32 v112, v112, v114
	v_add_f32_e32 v113, v113, v115
	v_mov_b32_e32 v114, v112
	v_mov_b32_e32 v115, v113
	s_nop 0
	v_permlane32_swap_b32_e32 v112, v114
	v_permlane32_swap_b32_e32 v113, v115
	s_and_saveexec_b64 s[2:3], s[8:9]
	v_pk_add_f32 v[112:113], v[112:113], v[114:115]
	ds_write_b64 v184, v[112:113] offset:512
	s_or_b64 exec, exec, s[2:3]
	v_add_f32_e32 v112, v92, v93
	v_add_f32_e32 v113, v94, v95
	v_add_f32_e32 v112, v112, v113
	v_mul_f32_e32 v113, v93, v93
	v_mul_f32_e32 v114, v95, v95
	v_fmac_f32_e32 v113, v92, v92
	v_fmac_f32_e32 v114, v94, v94
	v_add_f32_e32 v113, v113, v114
	v_add_f32_e32 v114, v96, v97
	v_add_f32_e32 v115, v98, v99
	v_add_f32_e32 v112, 0, v112
	v_add_f32_e32 v114, v114, v115
	v_add_f32_e32 v112, v114, v112
	v_mul_f32_e32 v114, v97, v97
	v_mul_f32_e32 v115, v99, v99
	v_fmac_f32_e32 v114, v96, v96
	v_fmac_f32_e32 v115, v98, v98
	v_add_f32_e32 v114, v114, v115
	v_add_f32_e32 v113, v113, v114
	v_add_f32_e32 v114, v84, v85
	v_add_f32_e32 v115, v86, v87
	v_add_f32_e32 v114, v114, v115
	v_add_f32_e32 v112, v114, v112
	v_mul_f32_e32 v114, v85, v85
	v_mul_f32_e32 v115, v87, v87
	v_fmac_f32_e32 v114, v84, v84
	v_fmac_f32_e32 v115, v86, v86
	v_add_f32_e32 v114, v114, v115
	v_add_f32_e32 v113, v114, v113
	v_add_f32_e32 v114, v88, v89
	v_add_f32_e32 v115, v90, v91
	v_add_f32_e32 v114, v114, v115
	v_add_f32_e32 v112, v114, v112
	v_mul_f32_e32 v114, v89, v89
	v_mul_f32_e32 v115, v91, v91
	v_fmac_f32_e32 v114, v88, v88
	v_fmac_f32_e32 v115, v90, v90
	v_add_f32_e32 v114, v114, v115
	v_add_f32_e32 v113, v114, v113
	v_mov_b32_e32 v114, v112
	v_mov_b32_e32 v115, v113
	s_nop 0
	v_permlane16_swap_b32_e32 v112, v114
	v_permlane16_swap_b32_e32 v113, v115
	v_add_f32_e32 v112, v112, v114
	v_add_f32_e32 v113, v113, v115
	v_mov_b32_e32 v114, v112
	v_mov_b32_e32 v115, v113
	s_nop 0
	v_permlane32_swap_b32_e32 v112, v114
	v_permlane32_swap_b32_e32 v113, v115
	s_and_saveexec_b64 s[2:3], s[8:9]
	v_pk_add_f32 v[112:113], v[112:113], v[114:115]
	ds_write_b64 v184, v[112:113] offset:1024
	s_or_b64 exec, exec, s[2:3]
	v_add_f32_e32 v112, v76, v77
	v_add_f32_e32 v113, v78, v79
	v_add_f32_e32 v112, v112, v113
	v_mul_f32_e32 v113, v77, v77
	v_mul_f32_e32 v114, v79, v79
	v_fmac_f32_e32 v113, v76, v76
	v_fmac_f32_e32 v114, v78, v78
	v_add_f32_e32 v113, v113, v114
	v_add_f32_e32 v114, v80, v81
	v_add_f32_e32 v115, v82, v83
	v_add_f32_e32 v112, 0, v112
	v_add_f32_e32 v114, v114, v115
	v_add_f32_e32 v112, v114, v112
	v_mul_f32_e32 v114, v81, v81
	v_mul_f32_e32 v115, v83, v83
	v_fmac_f32_e32 v114, v80, v80
	v_fmac_f32_e32 v115, v82, v82
	v_add_f32_e32 v114, v114, v115
	v_add_f32_e32 v113, v113, v114
	v_add_f32_e32 v114, v68, v69
	v_add_f32_e32 v115, v70, v71
	v_add_f32_e32 v114, v114, v115
	v_add_f32_e32 v112, v114, v112
	v_mul_f32_e32 v114, v69, v69
	v_mul_f32_e32 v115, v71, v71
	v_fmac_f32_e32 v114, v68, v68
	v_fmac_f32_e32 v115, v70, v70
	v_add_f32_e32 v114, v114, v115
	v_add_f32_e32 v113, v114, v113
	v_add_f32_e32 v114, v72, v73
	v_add_f32_e32 v115, v74, v75
	v_add_f32_e32 v114, v114, v115
	v_add_f32_e32 v112, v114, v112
	v_mul_f32_e32 v114, v73, v73
	v_mul_f32_e32 v115, v75, v75
	v_fmac_f32_e32 v114, v72, v72
	v_fmac_f32_e32 v115, v74, v74
	v_add_f32_e32 v114, v114, v115
	v_add_f32_e32 v113, v114, v113
	v_mov_b32_e32 v114, v112
	v_mov_b32_e32 v115, v113
	s_nop 0
	v_permlane16_swap_b32_e32 v112, v114
	v_permlane16_swap_b32_e32 v113, v115
	v_add_f32_e32 v112, v112, v114
	v_add_f32_e32 v113, v113, v115
	v_mov_b32_e32 v114, v112
	v_mov_b32_e32 v115, v113
	s_nop 0
	v_permlane32_swap_b32_e32 v112, v114
	v_permlane32_swap_b32_e32 v113, v115
	s_and_saveexec_b64 s[2:3], s[8:9]
	v_pk_add_f32 v[112:113], v[112:113], v[114:115]
	ds_write_b64 v184, v[112:113] offset:1536
	s_or_b64 exec, exec, s[2:3]
	v_add_f32_e32 v112, v60, v61
	v_add_f32_e32 v113, v62, v63
	v_add_f32_e32 v112, v112, v113
	v_mul_f32_e32 v113, v61, v61
	v_mul_f32_e32 v114, v63, v63
	v_fmac_f32_e32 v113, v60, v60
	v_fmac_f32_e32 v114, v62, v62
	v_add_f32_e32 v113, v113, v114
	v_add_f32_e32 v114, v64, v65
	v_add_f32_e32 v115, v66, v67
	v_add_f32_e32 v112, 0, v112
	v_add_f32_e32 v114, v114, v115
	v_add_f32_e32 v112, v114, v112
	v_mul_f32_e32 v114, v65, v65
	v_mul_f32_e32 v115, v67, v67
	v_fmac_f32_e32 v114, v64, v64
	v_fmac_f32_e32 v115, v66, v66
	v_add_f32_e32 v114, v114, v115
	v_add_f32_e32 v113, v113, v114
	v_add_f32_e32 v114, v52, v53
	v_add_f32_e32 v115, v54, v55
	v_add_f32_e32 v114, v114, v115
	v_add_f32_e32 v112, v114, v112
	v_mul_f32_e32 v114, v53, v53
	v_mul_f32_e32 v115, v55, v55
	v_fmac_f32_e32 v114, v52, v52
	v_fmac_f32_e32 v115, v54, v54
	v_add_f32_e32 v114, v114, v115
	v_add_f32_e32 v113, v114, v113
	v_add_f32_e32 v114, v56, v57
	v_add_f32_e32 v115, v58, v59
	v_add_f32_e32 v114, v114, v115
	v_add_f32_e32 v112, v114, v112
	v_mul_f32_e32 v114, v57, v57
	v_mul_f32_e32 v115, v59, v59
	v_fmac_f32_e32 v114, v56, v56
	v_fmac_f32_e32 v115, v58, v58
	v_add_f32_e32 v114, v114, v115
	v_add_f32_e32 v113, v114, v113
	v_mov_b32_e32 v114, v112
	v_mov_b32_e32 v115, v113
	s_nop 0
	v_permlane16_swap_b32_e32 v112, v114
	v_permlane16_swap_b32_e32 v113, v115
	v_add_f32_e32 v112, v112, v114
	v_add_f32_e32 v113, v113, v115
	v_mov_b32_e32 v114, v112
	v_mov_b32_e32 v115, v113
	s_nop 0
	v_permlane32_swap_b32_e32 v112, v114
	v_permlane32_swap_b32_e32 v113, v115
	s_and_saveexec_b64 s[2:3], s[8:9]
	v_pk_add_f32 v[112:113], v[112:113], v[114:115]
	ds_write_b64 v184, v[112:113] offset:4096
	s_or_b64 exec, exec, s[2:3]
	v_add_f32_e32 v112, v44, v45
	v_add_f32_e32 v113, v46, v47
	v_add_f32_e32 v112, v112, v113
	v_mul_f32_e32 v113, v45, v45
	v_mul_f32_e32 v114, v47, v47
	v_fmac_f32_e32 v113, v44, v44
	v_fmac_f32_e32 v114, v46, v46
	v_add_f32_e32 v113, v113, v114
	v_add_f32_e32 v114, v48, v49
	v_add_f32_e32 v115, v50, v51
	v_add_f32_e32 v112, 0, v112
	v_add_f32_e32 v114, v114, v115
	v_add_f32_e32 v112, v114, v112
	v_mul_f32_e32 v114, v49, v49
	v_mul_f32_e32 v115, v51, v51
	v_fmac_f32_e32 v114, v48, v48
	v_fmac_f32_e32 v115, v50, v50
	v_add_f32_e32 v114, v114, v115
	v_add_f32_e32 v113, v113, v114
	v_add_f32_e32 v114, v36, v37
	v_add_f32_e32 v115, v38, v39
	v_add_f32_e32 v114, v114, v115
	v_add_f32_e32 v112, v114, v112
	v_mul_f32_e32 v114, v37, v37
	v_mul_f32_e32 v115, v39, v39
	v_fmac_f32_e32 v114, v36, v36
	v_fmac_f32_e32 v115, v38, v38
	v_add_f32_e32 v114, v114, v115
	v_add_f32_e32 v113, v114, v113
	v_add_f32_e32 v114, v40, v41
	v_add_f32_e32 v115, v42, v43
	v_add_f32_e32 v114, v114, v115
	v_add_f32_e32 v112, v114, v112
	v_mul_f32_e32 v114, v41, v41
	v_mul_f32_e32 v115, v43, v43
	v_fmac_f32_e32 v114, v40, v40
	v_fmac_f32_e32 v115, v42, v42
	v_add_f32_e32 v114, v114, v115
	v_add_f32_e32 v113, v114, v113
	v_mov_b32_e32 v114, v112
	v_mov_b32_e32 v115, v113
	s_nop 0
	v_permlane16_swap_b32_e32 v112, v114
	v_permlane16_swap_b32_e32 v113, v115
	v_add_f32_e32 v112, v112, v114
	v_add_f32_e32 v113, v113, v115
	v_mov_b32_e32 v114, v112
	v_mov_b32_e32 v115, v113
	s_nop 0
	v_permlane32_swap_b32_e32 v112, v114
	v_permlane32_swap_b32_e32 v113, v115
	s_and_saveexec_b64 s[2:3], s[8:9]
	v_pk_add_f32 v[112:113], v[112:113], v[114:115]
	ds_write_b64 v184, v[112:113] offset:4608
	s_or_b64 exec, exec, s[2:3]
	v_add_f32_e32 v112, v28, v29
	v_add_f32_e32 v113, v30, v31
	v_add_f32_e32 v112, v112, v113
	v_mul_f32_e32 v113, v29, v29
	v_mul_f32_e32 v114, v31, v31
	v_fmac_f32_e32 v113, v28, v28
	v_fmac_f32_e32 v114, v30, v30
	v_add_f32_e32 v113, v113, v114
	v_add_f32_e32 v114, v32, v33
	v_add_f32_e32 v115, v34, v35
	v_add_f32_e32 v112, 0, v112
	v_add_f32_e32 v114, v114, v115
	v_add_f32_e32 v112, v114, v112
	v_mul_f32_e32 v114, v33, v33
	v_mul_f32_e32 v115, v35, v35
	v_fmac_f32_e32 v114, v32, v32
	v_fmac_f32_e32 v115, v34, v34
	v_add_f32_e32 v114, v114, v115
	v_add_f32_e32 v113, v113, v114
	v_add_f32_e32 v114, v20, v21
	v_add_f32_e32 v115, v22, v23
	v_add_f32_e32 v114, v114, v115
	v_add_f32_e32 v112, v114, v112
	v_mul_f32_e32 v114, v21, v21
	v_mul_f32_e32 v115, v23, v23
	v_fmac_f32_e32 v114, v20, v20
	v_fmac_f32_e32 v115, v22, v22
	v_add_f32_e32 v114, v114, v115
	v_add_f32_e32 v113, v114, v113
	v_add_f32_e32 v114, v24, v25
	v_add_f32_e32 v115, v26, v27
	v_add_f32_e32 v114, v114, v115
	v_add_f32_e32 v112, v114, v112
	v_mul_f32_e32 v114, v25, v25
	v_mul_f32_e32 v115, v27, v27
	v_fmac_f32_e32 v114, v24, v24
	v_fmac_f32_e32 v115, v26, v26
	v_add_f32_e32 v114, v114, v115
	v_add_f32_e32 v113, v114, v113
	v_mov_b32_e32 v114, v112
	v_mov_b32_e32 v115, v113
	s_nop 0
	v_permlane16_swap_b32_e32 v112, v114
	v_permlane16_swap_b32_e32 v113, v115
	v_add_f32_e32 v112, v112, v114
	v_add_f32_e32 v113, v113, v115
	v_mov_b32_e32 v114, v112
	v_mov_b32_e32 v115, v113
	s_nop 0
	v_permlane32_swap_b32_e32 v112, v114
	v_permlane32_swap_b32_e32 v113, v115
	s_and_saveexec_b64 s[2:3], s[8:9]
	v_pk_add_f32 v[112:113], v[112:113], v[114:115]
	ds_write_b64 v184, v[112:113] offset:5120
	s_or_b64 exec, exec, s[2:3]
	v_add_f32_e32 v112, v12, v13
	v_add_f32_e32 v113, v14, v15
	v_add_f32_e32 v112, v112, v113
	v_mul_f32_e32 v113, v13, v13
	v_mul_f32_e32 v114, v15, v15
	v_fmac_f32_e32 v113, v12, v12
	v_fmac_f32_e32 v114, v14, v14
	v_add_f32_e32 v113, v113, v114
	v_add_f32_e32 v114, v16, v17
	v_add_f32_e32 v115, v18, v19
	v_add_f32_e32 v112, 0, v112
	v_add_f32_e32 v114, v114, v115
	v_add_f32_e32 v112, v114, v112
	v_mul_f32_e32 v114, v17, v17
	v_mul_f32_e32 v115, v19, v19
	v_fmac_f32_e32 v114, v16, v16
	v_fmac_f32_e32 v115, v18, v18
	v_add_f32_e32 v114, v114, v115
	v_add_f32_e32 v113, v113, v114
	v_add_f32_e32 v114, v4, v5
	v_add_f32_e32 v115, v6, v7
	v_add_f32_e32 v114, v114, v115
	v_add_f32_e32 v112, v114, v112
	v_mul_f32_e32 v114, v5, v5
	v_mul_f32_e32 v115, v7, v7
	v_fmac_f32_e32 v114, v4, v4
	v_fmac_f32_e32 v115, v6, v6
	v_add_f32_e32 v114, v114, v115
	v_add_f32_e32 v113, v114, v113
	v_add_f32_e32 v114, v8, v9
	v_add_f32_e32 v115, v10, v11
	v_add_f32_e32 v114, v114, v115
	v_add_f32_e32 v112, v114, v112
	v_mul_f32_e32 v114, v9, v9
	v_mul_f32_e32 v115, v11, v11
	v_fmac_f32_e32 v114, v8, v8
	v_fmac_f32_e32 v115, v10, v10
	v_add_f32_e32 v114, v114, v115
	v_add_f32_e32 v113, v114, v113
	v_mov_b32_e32 v114, v112
	v_mov_b32_e32 v115, v113
	s_nop 0
	v_permlane16_swap_b32_e32 v112, v114
	v_permlane16_swap_b32_e32 v113, v115
	v_add_f32_e32 v112, v112, v114
	v_add_f32_e32 v113, v113, v115
	v_mov_b32_e32 v114, v112
	v_mov_b32_e32 v115, v113
	s_nop 0
	v_permlane32_swap_b32_e32 v112, v114
	v_permlane32_swap_b32_e32 v113, v115
	s_and_saveexec_b64 s[2:3], s[8:9]
	v_pk_add_f32 v[112:113], v[112:113], v[114:115]
	ds_write_b64 v184, v[112:113] offset:5632
	s_or_b64 exec, exec, s[2:3]
	s_waitcnt lgkmcnt(0)
	s_barrier
	s_add_u32 s14, s22, 0xac00000
	v_add_u32_e32 v170, s66, v180
	s_addc_u32 s15, s23, 0
	v_ashrrev_i32_e32 v171, 31, v170
	s_and_saveexec_b64 s[2:3], s[10:11]
	s_cbranch_execz .LBB0_257
	ds_read_b128 v[112:115], v183
	ds_read_b128 v[120:123], v183 offset:16
	s_ashr_i32 s83, s82, 31
	s_waitcnt lgkmcnt(1)
	v_mov_b32_e32 v124, v112
	s_waitcnt lgkmcnt(0)
	v_mov_b32_e32 v125, v120
	v_mov_b32_e32 v126, v114
	v_mov_b32_e32 v127, v122
	v_pk_add_f32 v[124:125], v[124:125], v[126:127]
	v_mov_b32_e32 v120, v113
	v_mov_b32_e32 v122, v115
	v_add_f32_e32 v114, v124, v125
	v_pk_add_f32 v[112:113], v[120:121], v[122:123]
	s_nop 0
	v_add_f32_e32 v113, v112, v113
	v_mul_f32_e32 v112, 0x3b800000, v114
	v_fma_f32 v113, -v114, v112, v113
	v_lshlrev_b64 v[114:115], 6, v[170:171]
	v_lshl_add_u64 v[114:115], s[14:15], 0, v[114:115]
	v_max_f32_e32 v113, 0, v113
	v_lshl_add_u64 v[114:115], s[82:83], 3, v[114:115]
	global_store_dwordx2 v[114:115], v[112:113], off sc1

.LBB0_647:
	v_readlane_b32 s5, v254, 35
	s_waitcnt lgkmcnt(0)
	s_add_u32 s5, s22, s5
	s_addc_u32 s19, s23, 0
	s_add_u32 s5, s5, 0x100000
	s_addc_u32 s49, s19, 0
	s_lshr_b32 s19, s72, 14
	s_add_i32 s19, s19, 8
	s_ashr_i32 s29, s18, 4
	s_and_b64 s[54:55], s[54:55], exec
	s_cselect_b32 s19, s19, s29
	s_lshl_b32 s29, s28, 8
	s_mul_hi_i32 s55, s19, 0x4800
	s_mul_i32 s54, s19, 0x4800
	s_or_b32 s63, s29, s51
	s_lshl_b64 s[54:55], s[54:55], 2
	v_or_b32_e32 v132, s63, v179
	s_add_u32 s66, s5, s54
	s_addc_u32 s67, s49, s55
	v_ashrrev_i32_e32 v133, 31, v132
	v_lshl_add_u64 v[132:133], v[132:133], 2, s[66:67]
	s_mov_b32 s19, 0xa000
	s_mov_b64 s[66:67], 0xa000
	v_add_co_u32_e32 v142, vcc, s19, v132
	v_lshl_add_u64 v[140:141], v[132:133], 0, s[66:67]
	s_nop 0
	v_addc_co_u32_e32 v143, vcc, 0, v133, vcc
	global_load_dwordx4 v[132:135], v[140:141], off offset:64
	global_load_dwordx4 v[136:139], v[140:141], off offset:512
	s_nop 0
	global_load_dwordx4 v[142:145], v[142:143], off
	s_nop 0
	global_load_dwordx4 v[154:157], v[140:141], off offset:576
	v_or3_b32 v140, v183, s51, v181
	v_add_u32_e32 v140, s29, v140
	v_ashrrev_i32_e32 v141, 31, v140
	v_lshl_add_u64 v[152:153], v[140:141], 2, s[60:61]
	v_readlane_b32 s60, v254, 54
	v_lshl_add_u64 v[140:141], v[152:153], 0, s[6:7]
	v_readlane_b32 s61, v254, 55
	global_load_dwordx4 v[146:149], v[140:141], off nt
	global_load_dwordx4 v[158:161], v[140:141], off offset:512 nt
	v_lshl_add_u64 v[140:141], v[152:153], 0, s[60:61]
	v_readlane_b32 s60, v254, 58
	global_load_dwordx4 v[174:177], v[140:141], off nt
	global_load_dwordx4 v[190:193], v[140:141], off offset:512 nt
	v_lshl_add_u64 v[140:141], v[152:153], 0, s[34:35]
	v_readlane_b32 s61, v254, 59
	global_load_dwordx4 v[194:197], v[140:141], off nt
	global_load_dwordx4 v[198:201], v[140:141], off offset:512 nt
	v_lshl_add_u64 v[140:141], v[152:153], 0, s[60:61]
	v_readlane_b32 s60, v254, 62
	global_load_dwordx4 v[202:205], v[140:141], off nt
	global_load_dwordx4 v[214:217], v[140:141], off offset:512 nt
	v_lshl_add_u64 v[140:141], v[152:153], 0, s[40:41]
	v_readlane_b32 s61, v254, 63
	global_load_dwordx4 v[218:221], v[140:141], off nt
	global_load_dwordx4 v[222:225], v[140:141], off offset:512 nt
	v_lshl_add_u64 v[140:141], v[152:153], 0, s[60:61]
	v_readlane_b32 s60, v255, 2
	global_load_dwordx4 v[226:229], v[140:141], off nt
	global_load_dwordx4 v[230:233], v[140:141], off offset:512 nt
	v_lshl_add_u64 v[140:141], v[152:153], 0, s[46:47]
	v_readlane_b32 s61, v255, 3
	global_load_dwordx4 v[234:237], v[140:141], off nt
	global_load_dwordx4 v[238:241], v[140:141], off offset:512 nt
	v_lshl_add_u64 v[140:141], v[152:153], 0, s[60:61]
	global_load_dwordx4 v[250:253], v[140:141], off nt
	global_load_dwordx4 v[206:209], v[140:141], off offset:512 nt
	s_waitcnt vmcnt(0)
	ds_write_b128 v182, v[146:149]
	ds_write_b128 v182, v[174:177] offset:1152
	ds_read_b128 v[146:149], v180
	ds_read_b128 v[174:177], v180 offset:64
	ds_write_b128 v182, v[158:161]
	ds_write_b128 v182, v[190:193] offset:1152
	ds_read_b128 v[158:161], v180
	ds_read_b128 v[190:193], v180 offset:64
	s_waitcnt lgkmcnt(5)
	v_pk_mul_f32 v[146:147], v[146:147], s[80:81] op_sel_hi:[1,0]
	v_pk_add_f32 v[142:143], v[142:143], 1.0 op_sel_hi:[1,0]
	ds_write_b128 v182, v[194:197]
	ds_write_b128 v182, v[202:205] offset:1152
	v_pk_add_f32 v[140:141], v[144:145], 1.0 op_sel_hi:[1,0]
	v_pk_fma_f32 v[128:129], v[128:129], v[142:143], v[146:147]
	s_waitcnt lgkmcnt(6)
	v_pk_mul_f32 v[144:145], v[176:177], s[80:81] op_sel_hi:[1,0]
	v_pk_mul_f32 v[146:147], v[174:175], s[80:81] op_sel_hi:[1,0]
	ds_read_b128 v[174:177], v180
	ds_read_b128 v[194:197], v180 offset:64
	v_pk_mul_f32 v[148:149], v[148:149], s[80:81] op_sel_hi:[1,0]
	v_pk_add_f32 v[150:151], v[132:133], 1.0 op_sel_hi:[1,0]
	v_pk_fma_f32 v[130:131], v[130:131], v[140:141], v[148:149]
	v_pk_add_f32 v[148:149], v[134:135], 1.0 op_sel_hi:[1,0]
	v_pk_fma_f32 v[132:133], v[124:125], v[150:151], v[146:147]
	v_pk_fma_f32 v[134:135], v[126:127], v[148:149], v[144:145]
	s_waitcnt lgkmcnt(5)
	v_pk_mul_f32 v[144:145], v[160:161], s[80:81] op_sel_hi:[1,0]
	v_pk_add_f32 v[124:125], v[138:139], 1.0 op_sel_hi:[1,0]
	ds_write_b128 v182, v[198:201]
	ds_write_b128 v182, v[214:217] offset:1152
	v_pk_mul_f32 v[146:147], v[158:159], s[80:81] op_sel_hi:[1,0]
	v_pk_fma_f32 v[138:139], v[122:123], v[124:125], v[144:145]
	s_waitcnt lgkmcnt(6)
	v_pk_mul_f32 v[144:145], v[192:193], s[80:81] op_sel_hi:[1,0]
	v_pk_mul_f32 v[162:163], v[190:191], s[80:81] op_sel_hi:[1,0]
	ds_read_b128 v[158:161], v180
	ds_read_b128 v[190:193], v180 offset:64
	v_pk_add_f32 v[126:127], v[136:137], 1.0 op_sel_hi:[1,0]
	v_pk_add_f32 v[122:123], v[154:155], 1.0 op_sel_hi:[1,0]
	v_pk_fma_f32 v[136:137], v[120:121], v[126:127], v[146:147]
	v_pk_add_f32 v[120:121], v[156:157], 1.0 op_sel_hi:[1,0]
	s_nop 0
	v_pk_fma_f32 v[146:147], v[106:107], v[120:121], v[144:145]
	v_pk_fma_f32 v[144:145], v[104:105], v[122:123], v[162:163]
	s_waitcnt lgkmcnt(5)
	v_pk_mul_f32 v[104:105], v[176:177], s[80:81] op_sel_hi:[1,0]
	v_pk_mul_f32 v[106:107], v[174:175], s[80:81] op_sel_hi:[1,0]
	v_pk_fma_f32 v[110:111], v[110:111], v[140:141], v[104:105]
	v_pk_fma_f32 v[108:109], v[108:109], v[142:143], v[106:107]
	s_waitcnt lgkmcnt(4)
	v_pk_mul_f32 v[104:105], v[196:197], s[80:81] op_sel_hi:[1,0]
	v_pk_mul_f32 v[106:107], v[194:195], s[80:81] op_sel_hi:[1,0]
	v_pk_fma_f32 v[118:119], v[118:119], v[148:149], v[104:105]
	v_pk_fma_f32 v[116:117], v[116:117], v[150:151], v[106:107]
	s_waitcnt lgkmcnt(1)
	v_pk_mul_f32 v[104:105], v[160:161], s[80:81] op_sel_hi:[1,0]
	v_pk_mul_f32 v[106:107], v[158:159], s[80:81] op_sel_hi:[1,0]
	v_pk_fma_f32 v[102:103], v[102:103], v[124:125], v[104:105]
	s_waitcnt lgkmcnt(0)
	v_pk_mul_f32 v[104:105], v[192:193], s[80:81] op_sel_hi:[1,0]
	v_pk_mul_f32 v[154:155], v[190:191], s[80:81] op_sel_hi:[1,0]
	v_pk_fma_f32 v[100:101], v[100:101], v[126:127], v[106:107]
	v_pk_fma_f32 v[106:107], v[98:99], v[120:121], v[104:105]
	v_pk_fma_f32 v[104:105], v[96:97], v[122:123], v[154:155]
	v_readlane_b32 s60, v255, 6
	v_lshl_add_u64 v[96:97], v[152:153], 0, s[52:53]
	v_readlane_b32 s61, v255, 7
	global_load_dwordx4 v[154:157], v[96:97], off nt
	global_load_dwordx4 v[158:161], v[96:97], off offset:512 nt
	v_lshl_add_u64 v[96:97], v[152:153], 0, s[60:61]
	v_readlane_b32 s60, v255, 12
	global_load_dwordx4 v[174:177], v[96:97], off nt
	global_load_dwordx4 v[190:193], v[96:97], off offset:512 nt
	v_lshl_add_u64 v[96:97], v[152:153], 0, s[58:59]
	v_readlane_b32 s61, v255, 13
	global_load_dwordx4 v[194:197], v[96:97], off nt
	global_load_dwordx4 v[198:201], v[96:97], off offset:512 nt
	v_lshl_add_u64 v[96:97], v[152:153], 0, s[60:61]
	global_load_dwordx4 v[202:205], v[96:97], off nt
	global_load_dwordx4 v[214:217], v[96:97], off offset:512 nt
	ds_write_b128 v182, v[218:221]
	ds_write_b128 v182, v[226:229] offset:1152
	ds_read_b128 v[96:99], v180
	ds_read_b128 v[218:221], v180 offset:64
	ds_write_b128 v182, v[222:225]
	ds_write_b128 v182, v[230:233] offset:1152
	ds_read_b128 v[222:225], v180
	ds_read_b128 v[226:229], v180 offset:64
	ds_write_b128 v182, v[234:237]
	ds_write_b128 v182, v[250:253] offset:1152
	ds_read_b128 v[230:233], v180
	ds_read_b128 v[234:237], v180 offset:64
	s_waitcnt lgkmcnt(9)
	v_pk_mul_f32 v[96:97], v[96:97], s[80:81] op_sel_hi:[1,0]
	v_pk_mul_f32 v[98:99], v[98:99], s[80:81] op_sel_hi:[1,0]
	v_pk_fma_f32 v[92:93], v[92:93], v[142:143], v[96:97]
	s_waitcnt lgkmcnt(8)
	v_pk_mul_f32 v[96:97], v[220:221], s[80:81] op_sel_hi:[1,0]
	v_pk_mul_f32 v[162:163], v[218:219], s[80:81] op_sel_hi:[1,0]
	v_pk_fma_f32 v[94:95], v[94:95], v[140:141], v[98:99]
	v_pk_fma_f32 v[98:99], v[90:91], v[148:149], v[96:97]
	v_pk_fma_f32 v[96:97], v[88:89], v[150:151], v[162:163]
	ds_write_b128 v182, v[238:241]
	ds_write_b128 v182, v[206:209] offset:1152
	ds_read_b128 v[206:209], v180
	ds_read_b128 v[218:221], v180 offset:64
	s_waitcnt lgkmcnt(9)
	v_pk_mul_f32 v[88:89], v[224:225], s[80:81] op_sel_hi:[1,0]
	v_pk_mul_f32 v[90:91], v[222:223], s[80:81] op_sel_hi:[1,0]
	v_pk_fma_f32 v[86:87], v[86:87], v[124:125], v[88:89]
	s_waitcnt lgkmcnt(8)
	v_pk_mul_f32 v[88:89], v[228:229], s[80:81] op_sel_hi:[1,0]
	v_pk_mul_f32 v[162:163], v[226:227], s[80:81] op_sel_hi:[1,0]
	v_pk_fma_f32 v[84:85], v[84:85], v[126:127], v[90:91]
	v_pk_fma_f32 v[90:91], v[74:75], v[120:121], v[88:89]
	v_pk_fma_f32 v[88:89], v[72:73], v[122:123], v[162:163]
	s_waitcnt lgkmcnt(5)
	v_pk_mul_f32 v[72:73], v[232:233], s[80:81] op_sel_hi:[1,0]
	v_pk_mul_f32 v[74:75], v[230:231], s[80:81] op_sel_hi:[1,0]
	v_pk_fma_f32 v[78:79], v[78:79], v[140:141], v[72:73]
	v_pk_fma_f32 v[76:77], v[76:77], v[142:143], v[74:75]
	s_waitcnt lgkmcnt(4)
	v_pk_mul_f32 v[72:73], v[236:237], s[80:81] op_sel_hi:[1,0]
	v_pk_mul_f32 v[74:75], v[234:235], s[80:81] op_sel_hi:[1,0]
	v_pk_fma_f32 v[82:83], v[82:83], v[148:149], v[72:73]
	v_pk_fma_f32 v[80:81], v[80:81], v[150:151], v[74:75]
	s_waitcnt lgkmcnt(1)
	v_pk_mul_f32 v[72:73], v[208:209], s[80:81] op_sel_hi:[1,0]
	v_pk_mul_f32 v[74:75], v[206:207], s[80:81] op_sel_hi:[1,0]
	v_pk_fma_f32 v[70:71], v[70:71], v[124:125], v[72:73]
	s_waitcnt lgkmcnt(0)
	v_pk_mul_f32 v[72:73], v[220:221], s[80:81] op_sel_hi:[1,0]
	v_pk_mul_f32 v[162:163], v[218:219], s[80:81] op_sel_hi:[1,0]
	v_pk_fma_f32 v[68:69], v[68:69], v[126:127], v[74:75]
	v_pk_fma_f32 v[74:75], v[66:67], v[120:121], v[72:73]
	v_pk_fma_f32 v[72:73], v[64:65], v[122:123], v[162:163]
	v_readlane_b32 s60, v254, 40
	v_lshl_add_u64 v[64:65], v[152:153], 0, s[64:65]
	v_readlane_b32 s61, v254, 41
	global_load_dwordx4 v[206:209], v[64:65], off nt
	global_load_dwordx4 v[218:221], v[64:65], off offset:512 nt
	v_lshl_add_u64 v[64:65], v[152:153], 0, s[60:61]
	v_readlane_b32 s60, v254, 42
	global_load_dwordx4 v[222:225], v[64:65], off nt
	global_load_dwordx4 v[226:229], v[64:65], off offset:512 nt
	v_lshl_add_u64 v[64:65], v[152:153], 0, s[78:79]
	v_readlane_b32 s61, v254, 43
	global_load_dwordx4 v[230:233], v[64:65], off nt
	global_load_dwordx4 v[234:237], v[64:65], off offset:512 nt
	v_lshl_add_u64 v[64:65], v[152:153], 0, s[60:61]
	global_load_dwordx4 v[238:241], v[64:65], off nt
	global_load_dwordx4 v[250:253], v[64:65], off offset:512 nt
	s_waitcnt vmcnt(15)
	ds_write_b128 v182, v[154:157]
	s_waitcnt vmcnt(13)
	ds_write_b128 v182, v[174:177] offset:1152
	ds_read_b128 v[64:67], v180
	ds_read_b128 v[152:155], v180 offset:64
	ds_write_b128 v182, v[158:161]
	s_waitcnt vmcnt(12)
	ds_write_b128 v182, v[190:193] offset:1152
	ds_read_b128 v[156:159], v180
	ds_read_b128 v[160:163], v180 offset:64
	s_waitcnt vmcnt(11)
	ds_write_b128 v182, v[194:197]
	s_waitcnt vmcnt(9)
	ds_write_b128 v182, v[202:205] offset:1152
	ds_read_b128 v[174:177], v180
	ds_read_b128 v[190:193], v180 offset:64
	s_waitcnt lgkmcnt(9)
	v_pk_mul_f32 v[64:65], v[64:65], s[80:81] op_sel_hi:[1,0]
	v_pk_mul_f32 v[66:67], v[66:67], s[80:81] op_sel_hi:[1,0]
	v_pk_fma_f32 v[60:61], v[60:61], v[142:143], v[64:65]
	s_waitcnt lgkmcnt(8)
	v_pk_mul_f32 v[64:65], v[154:155], s[80:81] op_sel_hi:[1,0]
	v_pk_mul_f32 v[152:153], v[152:153], s[80:81] op_sel_hi:[1,0]
	v_pk_fma_f32 v[62:63], v[62:63], v[140:141], v[66:67]
	v_pk_fma_f32 v[66:67], v[58:59], v[148:149], v[64:65]
	v_pk_fma_f32 v[64:65], v[56:57], v[150:151], v[152:153]
	ds_write_b128 v182, v[198:201]
	s_waitcnt vmcnt(8)
	ds_write_b128 v182, v[214:217] offset:1152
	s_waitcnt lgkmcnt(7)
	v_pk_mul_f32 v[56:57], v[158:159], s[80:81] op_sel_hi:[1,0]
	v_pk_mul_f32 v[58:59], v[156:157], s[80:81] op_sel_hi:[1,0]
	ds_read_b128 v[152:155], v180
	ds_read_b128 v[156:159], v180 offset:64
	v_pk_fma_f32 v[54:55], v[54:55], v[124:125], v[56:57]
	s_waitcnt lgkmcnt(8)
	v_pk_mul_f32 v[56:57], v[162:163], s[80:81] op_sel_hi:[1,0]
	v_pk_mul_f32 v[160:161], v[160:161], s[80:81] op_sel_hi:[1,0]
	v_pk_fma_f32 v[52:53], v[52:53], v[126:127], v[58:59]
	v_pk_fma_f32 v[58:59], v[42:43], v[120:121], v[56:57]
	v_pk_fma_f32 v[56:57], v[40:41], v[122:123], v[160:161]
	s_waitcnt lgkmcnt(5)
	v_pk_mul_f32 v[40:41], v[176:177], s[80:81] op_sel_hi:[1,0]
	v_pk_mul_f32 v[42:43], v[174:175], s[80:81] op_sel_hi:[1,0]
	v_pk_fma_f32 v[46:47], v[46:47], v[140:141], v[40:41]
	v_pk_fma_f32 v[44:45], v[44:45], v[142:143], v[42:43]
	s_waitcnt lgkmcnt(4)
	v_pk_mul_f32 v[40:41], v[192:193], s[80:81] op_sel_hi:[1,0]
	v_pk_mul_f32 v[42:43], v[190:191], s[80:81] op_sel_hi:[1,0]
	v_pk_fma_f32 v[50:51], v[50:51], v[148:149], v[40:41]
	v_pk_fma_f32 v[48:49], v[48:49], v[150:151], v[42:43]
	s_waitcnt lgkmcnt(1)
	v_pk_mul_f32 v[40:41], v[154:155], s[80:81] op_sel_hi:[1,0]
	v_pk_mul_f32 v[42:43], v[152:153], s[80:81] op_sel_hi:[1,0]
	v_pk_fma_f32 v[38:39], v[38:39], v[124:125], v[40:41]
	s_waitcnt lgkmcnt(0)
	v_pk_mul_f32 v[40:41], v[158:159], s[80:81] op_sel_hi:[1,0]
	v_pk_mul_f32 v[152:153], v[156:157], s[80:81] op_sel_hi:[1,0]
	v_pk_fma_f32 v[36:37], v[36:37], v[126:127], v[42:43]
	v_pk_fma_f32 v[42:43], v[34:35], v[120:121], v[40:41]
	v_pk_fma_f32 v[40:41], v[32:33], v[122:123], v[152:153]
	s_nop 0
	s_waitcnt vmcnt(7)
	ds_write_b128 v182, v[206:209]
	s_waitcnt vmcnt(5)
	ds_write_b128 v182, v[222:225] offset:1152
	ds_read_b128 v[32:35], v180
	ds_read_b128 v[152:155], v180 offset:64
	ds_write_b128 v182, v[218:221]
	s_waitcnt vmcnt(4)
	ds_write_b128 v182, v[226:229] offset:1152
	ds_read_b128 v[156:159], v180
	ds_read_b128 v[160:163], v180 offset:64
	s_waitcnt vmcnt(3)
	ds_write_b128 v182, v[230:233]
	s_waitcnt vmcnt(1)
	ds_write_b128 v182, v[238:241] offset:1152
	ds_read_b128 v[174:177], v180
	ds_read_b128 v[190:193], v180 offset:64
	s_waitcnt lgkmcnt(9)
	v_pk_mul_f32 v[32:33], v[32:33], s[80:81] op_sel_hi:[1,0]
	v_pk_mul_f32 v[34:35], v[34:35], s[80:81] op_sel_hi:[1,0]
	v_pk_fma_f32 v[28:29], v[28:29], v[142:143], v[32:33]
	s_waitcnt lgkmcnt(8)
	v_pk_mul_f32 v[32:33], v[154:155], s[80:81] op_sel_hi:[1,0]
	v_pk_mul_f32 v[152:153], v[152:153], s[80:81] op_sel_hi:[1,0]
	v_pk_fma_f32 v[30:31], v[30:31], v[140:141], v[34:35]
	v_pk_fma_f32 v[34:35], v[26:27], v[148:149], v[32:33]
	v_pk_fma_f32 v[32:33], v[24:25], v[150:151], v[152:153]
	ds_write_b128 v182, v[234:237]
	s_waitcnt vmcnt(0)
	ds_write_b128 v182, v[250:253] offset:1152
	s_waitcnt lgkmcnt(7)
	v_pk_mul_f32 v[24:25], v[158:159], s[80:81] op_sel_hi:[1,0]
	v_pk_mul_f32 v[26:27], v[156:157], s[80:81] op_sel_hi:[1,0]
	ds_read_b128 v[152:155], v180
	ds_read_b128 v[156:159], v180 offset:64
	v_pk_fma_f32 v[22:23], v[22:23], v[124:125], v[24:25]
	s_waitcnt lgkmcnt(8)
	v_pk_mul_f32 v[24:25], v[162:163], s[80:81] op_sel_hi:[1,0]
	v_pk_mul_f32 v[160:161], v[160:161], s[80:81] op_sel_hi:[1,0]
	v_pk_fma_f32 v[20:21], v[20:21], v[126:127], v[26:27]
	v_pk_fma_f32 v[26:27], v[14:15], v[120:121], v[24:25]
	v_pk_fma_f32 v[24:25], v[12:13], v[122:123], v[160:161]
	s_waitcnt lgkmcnt(5)
	v_pk_mul_f32 v[12:13], v[176:177], s[80:81] op_sel_hi:[1,0]
	v_pk_mul_f32 v[160:161], v[174:175], s[80:81] op_sel_hi:[1,0]
	v_pk_fma_f32 v[14:15], v[114:115], v[140:141], v[12:13]
	v_pk_fma_f32 v[12:13], v[112:113], v[142:143], v[160:161]
	s_waitcnt lgkmcnt(4)
	v_pk_mul_f32 v[112:113], v[192:193], s[80:81] op_sel_hi:[1,0]
	v_pk_mul_f32 v[114:115], v[190:191], s[80:81] op_sel_hi:[1,0]
	v_pk_fma_f32 v[18:19], v[18:19], v[148:149], v[112:113]
	v_pk_fma_f32 v[16:17], v[16:17], v[150:151], v[114:115]
	s_waitcnt lgkmcnt(1)
	v_pk_mul_f32 v[112:113], v[154:155], s[80:81] op_sel_hi:[1,0]
	v_pk_mul_f32 v[114:115], v[152:153], s[80:81] op_sel_hi:[1,0]
	v_pk_fma_f32 v[6:7], v[6:7], v[124:125], v[112:113]
	s_waitcnt lgkmcnt(0)
	v_pk_mul_f32 v[112:113], v[158:159], s[80:81] op_sel_hi:[1,0]
	v_pk_fma_f32 v[4:5], v[4:5], v[126:127], v[114:115]
	v_pk_mul_f32 v[114:115], v[156:157], s[80:81] op_sel_hi:[1,0]
	v_pk_fma_f32 v[10:11], v[10:11], v[120:121], v[112:113]
	v_add_f32_e32 v112, v128, v129
	v_add_f32_e32 v113, v130, v131
	v_pk_fma_f32 v[8:9], v[8:9], v[122:123], v[114:115]
	v_add_f32_e32 v112, v112, v113
	v_mul_f32_e32 v113, v129, v129
	v_mul_f32_e32 v114, v131, v131
	v_fmac_f32_e32 v113, v128, v128
	v_fmac_f32_e32 v114, v130, v130
	v_add_f32_e32 v113, v113, v114
	v_add_f32_e32 v114, v132, v133
	v_add_f32_e32 v115, v134, v135
	v_add_f32_e32 v112, 0, v112
	v_add_f32_e32 v114, v114, v115
	v_add_f32_e32 v112, v114, v112
	v_mul_f32_e32 v114, v133, v133
	v_mul_f32_e32 v115, v135, v135
	v_fmac_f32_e32 v114, v132, v132
	v_fmac_f32_e32 v115, v134, v134
	v_add_f32_e32 v114, v114, v115
	v_add_f32_e32 v113, v113, v114
	v_add_f32_e32 v114, v136, v137
	v_add_f32_e32 v115, v138, v139
	v_add_f32_e32 v114, v114, v115
	v_add_f32_e32 v112, v114, v112
	v_mul_f32_e32 v114, v137, v137
	v_mul_f32_e32 v115, v139, v139
	v_fmac_f32_e32 v114, v136, v136
	v_fmac_f32_e32 v115, v138, v138
	v_add_f32_e32 v114, v114, v115
	v_add_f32_e32 v113, v114, v113
	v_add_f32_e32 v114, v144, v145
	v_add_f32_e32 v115, v146, v147
	v_add_f32_e32 v114, v114, v115
	v_add_f32_e32 v112, v114, v112
	v_mul_f32_e32 v114, v145, v145
	v_mul_f32_e32 v115, v147, v147
	v_fmac_f32_e32 v114, v144, v144
	v_fmac_f32_e32 v115, v146, v146
	v_add_f32_e32 v114, v114, v115
	v_add_f32_e32 v113, v114, v113
	ds_swizzle_b32 v114, v112 offset:swizzle(SWAP,16)
	ds_swizzle_b32 v115, v113 offset:swizzle(SWAP,16)
	s_waitcnt lgkmcnt(1)
	v_add_f32_e32 v112, v112, v114
	s_waitcnt lgkmcnt(0)
	v_add_f32_e32 v113, v113, v115
	v_mov_b32_e32 v114, v112
	v_mov_b32_e32 v115, v113
	s_nop 0
	v_permlane32_swap_b32_e32 v112, v114
	v_permlane32_swap_b32_e32 v113, v115
	s_and_saveexec_b64 s[60:61], s[8:9]
	v_pk_add_f32 v[112:113], v[112:113], v[114:115]
	ds_write_b64 v188, v[112:113]
	s_or_b64 exec, exec, s[60:61]
	v_add_f32_e32 v112, v108, v109
	v_add_f32_e32 v113, v110, v111
	v_add_f32_e32 v112, v112, v113
	v_mul_f32_e32 v113, v109, v109
	v_mul_f32_e32 v114, v111, v111
	v_fmac_f32_e32 v113, v108, v108
	v_fmac_f32_e32 v114, v110, v110
	v_add_f32_e32 v113, v113, v114
	v_add_f32_e32 v114, v116, v117
	v_add_f32_e32 v115, v118, v119
	v_add_f32_e32 v112, 0, v112
	v_add_f32_e32 v114, v114, v115
	v_add_f32_e32 v112, v114, v112
	v_mul_f32_e32 v114, v117, v117
	v_mul_f32_e32 v115, v119, v119
	v_fmac_f32_e32 v114, v116, v116
	v_fmac_f32_e32 v115, v118, v118
	v_add_f32_e32 v114, v114, v115
	v_add_f32_e32 v113, v113, v114
	v_add_f32_e32 v114, v100, v101
	v_add_f32_e32 v115, v102, v103
	v_add_f32_e32 v114, v114, v115
	v_add_f32_e32 v112, v114, v112
	v_mul_f32_e32 v114, v101, v101
	v_mul_f32_e32 v115, v103, v103
	v_fmac_f32_e32 v114, v100, v100
	v_fmac_f32_e32 v115, v102, v102
	v_add_f32_e32 v114, v114, v115
	v_add_f32_e32 v113, v114, v113
	v_add_f32_e32 v114, v104, v105
	v_add_f32_e32 v115, v106, v107
	v_add_f32_e32 v114, v114, v115
	v_add_f32_e32 v112, v114, v112
	v_mul_f32_e32 v114, v105, v105
	v_mul_f32_e32 v115, v107, v107
	v_fmac_f32_e32 v114, v104, v104
	v_fmac_f32_e32 v115, v106, v106
	v_add_f32_e32 v114, v114, v115
	v_add_f32_e32 v113, v114, v113
	v_mov_b32_e32 v114, v112
	v_mov_b32_e32 v115, v113
	s_nop 0
	v_permlane16_swap_b32_e32 v112, v114
	v_permlane16_swap_b32_e32 v113, v115
	v_add_f32_e32 v112, v112, v114
	v_add_f32_e32 v113, v113, v115
	v_mov_b32_e32 v114, v112
	v_mov_b32_e32 v115, v113
	s_nop 0
	v_permlane32_swap_b32_e32 v112, v114
	v_permlane32_swap_b32_e32 v113, v115
	s_and_saveexec_b64 s[60:61], s[8:9]
	v_pk_add_f32 v[112:113], v[112:113], v[114:115]
	ds_write_b64 v188, v[112:113] offset:512
	s_or_b64 exec, exec, s[60:61]
	v_add_f32_e32 v112, v92, v93
	v_add_f32_e32 v113, v94, v95
	v_add_f32_e32 v112, v112, v113
	v_mul_f32_e32 v113, v93, v93
	v_mul_f32_e32 v114, v95, v95
	v_fmac_f32_e32 v113, v92, v92
	v_fmac_f32_e32 v114, v94, v94
	v_add_f32_e32 v113, v113, v114
	v_add_f32_e32 v114, v96, v97
	v_add_f32_e32 v115, v98, v99
	v_add_f32_e32 v112, 0, v112
	v_add_f32_e32 v114, v114, v115
	v_add_f32_e32 v112, v114, v112
	v_mul_f32_e32 v114, v97, v97
	v_mul_f32_e32 v115, v99, v99
	v_fmac_f32_e32 v114, v96, v96
	v_fmac_f32_e32 v115, v98, v98
	v_add_f32_e32 v114, v114, v115
	v_add_f32_e32 v113, v113, v114
	v_add_f32_e32 v114, v84, v85
	v_add_f32_e32 v115, v86, v87
	v_add_f32_e32 v114, v114, v115
	v_add_f32_e32 v112, v114, v112
	v_mul_f32_e32 v114, v85, v85
	v_mul_f32_e32 v115, v87, v87
	v_fmac_f32_e32 v114, v84, v84
	v_fmac_f32_e32 v115, v86, v86
	v_add_f32_e32 v114, v114, v115
	v_add_f32_e32 v113, v114, v113
	v_add_f32_e32 v114, v88, v89
	v_add_f32_e32 v115, v90, v91
	v_add_f32_e32 v114, v114, v115
	v_add_f32_e32 v112, v114, v112
	v_mul_f32_e32 v114, v89, v89
	v_mul_f32_e32 v115, v91, v91
	v_fmac_f32_e32 v114, v88, v88
	v_fmac_f32_e32 v115, v90, v90
	v_add_f32_e32 v114, v114, v115
	v_add_f32_e32 v113, v114, v113
	v_mov_b32_e32 v114, v112
	v_mov_b32_e32 v115, v113
	s_nop 0
	v_permlane16_swap_b32_e32 v112, v114
	v_permlane16_swap_b32_e32 v113, v115
	v_add_f32_e32 v112, v112, v114
	v_add_f32_e32 v113, v113, v115
	v_mov_b32_e32 v114, v112
	v_mov_b32_e32 v115, v113
	s_nop 0
	v_permlane32_swap_b32_e32 v112, v114
	v_permlane32_swap_b32_e32 v113, v115
	s_and_saveexec_b64 s[60:61], s[8:9]
	v_pk_add_f32 v[112:113], v[112:113], v[114:115]
	ds_write_b64 v188, v[112:113] offset:1024
	s_or_b64 exec, exec, s[60:61]
	v_add_f32_e32 v112, v76, v77
	v_add_f32_e32 v113, v78, v79
	v_add_f32_e32 v112, v112, v113
	v_mul_f32_e32 v113, v77, v77
	v_mul_f32_e32 v114, v79, v79
	v_fmac_f32_e32 v113, v76, v76
	v_fmac_f32_e32 v114, v78, v78
	v_add_f32_e32 v113, v113, v114
	v_add_f32_e32 v114, v80, v81
	v_add_f32_e32 v115, v82, v83
	v_add_f32_e32 v112, 0, v112
	v_add_f32_e32 v114, v114, v115
	v_add_f32_e32 v112, v114, v112
	v_mul_f32_e32 v114, v81, v81
	v_mul_f32_e32 v115, v83, v83
	v_fmac_f32_e32 v114, v80, v80
	v_fmac_f32_e32 v115, v82, v82
	v_add_f32_e32 v114, v114, v115
	v_add_f32_e32 v113, v113, v114
	v_add_f32_e32 v114, v68, v69
	v_add_f32_e32 v115, v70, v71
	v_add_f32_e32 v114, v114, v115
	v_add_f32_e32 v112, v114, v112
	v_mul_f32_e32 v114, v69, v69
	v_mul_f32_e32 v115, v71, v71
	v_fmac_f32_e32 v114, v68, v68
	v_fmac_f32_e32 v115, v70, v70
	v_add_f32_e32 v114, v114, v115
	v_add_f32_e32 v113, v114, v113
	v_add_f32_e32 v114, v72, v73
	v_add_f32_e32 v115, v74, v75
	v_add_f32_e32 v114, v114, v115
	v_add_f32_e32 v112, v114, v112
	v_mul_f32_e32 v114, v73, v73
	v_mul_f32_e32 v115, v75, v75
	v_fmac_f32_e32 v114, v72, v72
	v_fmac_f32_e32 v115, v74, v74
	v_add_f32_e32 v114, v114, v115
	v_add_f32_e32 v113, v114, v113
	v_mov_b32_e32 v114, v112
	v_mov_b32_e32 v115, v113
	s_nop 0
	v_permlane16_swap_b32_e32 v112, v114
	v_permlane16_swap_b32_e32 v113, v115
	v_add_f32_e32 v112, v112, v114
	v_add_f32_e32 v113, v113, v115
	v_mov_b32_e32 v114, v112
	v_mov_b32_e32 v115, v113
	s_nop 0
	v_permlane32_swap_b32_e32 v112, v114
	v_permlane32_swap_b32_e32 v113, v115
	s_and_saveexec_b64 s[60:61], s[8:9]
	v_pk_add_f32 v[112:113], v[112:113], v[114:115]
	ds_write_b64 v188, v[112:113] offset:1536
	s_or_b64 exec, exec, s[60:61]
	v_add_f32_e32 v112, v60, v61
	v_add_f32_e32 v113, v62, v63
	v_add_f32_e32 v112, v112, v113
	v_mul_f32_e32 v113, v61, v61
	v_mul_f32_e32 v114, v63, v63
	v_fmac_f32_e32 v113, v60, v60
	v_fmac_f32_e32 v114, v62, v62
	v_add_f32_e32 v113, v113, v114
	v_add_f32_e32 v114, v64, v65
	v_add_f32_e32 v115, v66, v67
	v_add_f32_e32 v112, 0, v112
	v_add_f32_e32 v114, v114, v115
	v_add_f32_e32 v112, v114, v112
	v_mul_f32_e32 v114, v65, v65
	v_mul_f32_e32 v115, v67, v67
	v_fmac_f32_e32 v114, v64, v64
	v_fmac_f32_e32 v115, v66, v66
	v_add_f32_e32 v114, v114, v115
	v_add_f32_e32 v113, v113, v114
	v_add_f32_e32 v114, v52, v53
	v_add_f32_e32 v115, v54, v55
	v_add_f32_e32 v114, v114, v115
	v_add_f32_e32 v112, v114, v112
	v_mul_f32_e32 v114, v53, v53
	v_mul_f32_e32 v115, v55, v55
	v_fmac_f32_e32 v114, v52, v52
	v_fmac_f32_e32 v115, v54, v54
	v_add_f32_e32 v114, v114, v115
	v_add_f32_e32 v113, v114, v113
	v_add_f32_e32 v114, v56, v57
	v_add_f32_e32 v115, v58, v59
	v_add_f32_e32 v114, v114, v115
	v_add_f32_e32 v112, v114, v112
	v_mul_f32_e32 v114, v57, v57
	v_mul_f32_e32 v115, v59, v59
	v_fmac_f32_e32 v114, v56, v56
	v_fmac_f32_e32 v115, v58, v58
	v_add_f32_e32 v114, v114, v115
	v_add_f32_e32 v113, v114, v113
	v_mov_b32_e32 v114, v112
	v_mov_b32_e32 v115, v113
	s_nop 0
	v_permlane16_swap_b32_e32 v112, v114
	v_permlane16_swap_b32_e32 v113, v115
	v_add_f32_e32 v112, v112, v114
	v_add_f32_e32 v113, v113, v115
	v_mov_b32_e32 v114, v112
	v_mov_b32_e32 v115, v113
	s_nop 0
	v_permlane32_swap_b32_e32 v112, v114
	v_permlane32_swap_b32_e32 v113, v115
	s_and_saveexec_b64 s[60:61], s[8:9]
	v_pk_add_f32 v[112:113], v[112:113], v[114:115]
	ds_write_b64 v188, v[112:113] offset:4096
	s_or_b64 exec, exec, s[60:61]
	v_add_f32_e32 v112, v44, v45
	v_add_f32_e32 v113, v46, v47
	v_add_f32_e32 v112, v112, v113
	v_mul_f32_e32 v113, v45, v45
	v_mul_f32_e32 v114, v47, v47
	v_fmac_f32_e32 v113, v44, v44
	v_fmac_f32_e32 v114, v46, v46
	v_add_f32_e32 v113, v113, v114
	v_add_f32_e32 v114, v48, v49
	v_add_f32_e32 v115, v50, v51
	v_add_f32_e32 v112, 0, v112
	v_add_f32_e32 v114, v114, v115
	v_add_f32_e32 v112, v114, v112
	v_mul_f32_e32 v114, v49, v49
	v_mul_f32_e32 v115, v51, v51
	v_fmac_f32_e32 v114, v48, v48
	v_fmac_f32_e32 v115, v50, v50
	v_add_f32_e32 v114, v114, v115
	v_add_f32_e32 v113, v113, v114
	v_add_f32_e32 v114, v36, v37
	v_add_f32_e32 v115, v38, v39
	v_add_f32_e32 v114, v114, v115
	v_add_f32_e32 v112, v114, v112
	v_mul_f32_e32 v114, v37, v37
	v_mul_f32_e32 v115, v39, v39
	v_fmac_f32_e32 v114, v36, v36
	v_fmac_f32_e32 v115, v38, v38
	v_add_f32_e32 v114, v114, v115
	v_add_f32_e32 v113, v114, v113
	v_add_f32_e32 v114, v40, v41
	v_add_f32_e32 v115, v42, v43
	v_add_f32_e32 v114, v114, v115
	v_add_f32_e32 v112, v114, v112
	v_mul_f32_e32 v114, v41, v41
	v_mul_f32_e32 v115, v43, v43
	v_fmac_f32_e32 v114, v40, v40
	v_fmac_f32_e32 v115, v42, v42
	v_add_f32_e32 v114, v114, v115
	v_add_f32_e32 v113, v114, v113
	v_mov_b32_e32 v114, v112
	v_mov_b32_e32 v115, v113
	s_nop 0
	v_permlane16_swap_b32_e32 v112, v114
	v_permlane16_swap_b32_e32 v113, v115
	v_add_f32_e32 v112, v112, v114
	v_add_f32_e32 v113, v113, v115
	v_mov_b32_e32 v114, v112
	v_mov_b32_e32 v115, v113
	s_nop 0
	v_permlane32_swap_b32_e32 v112, v114
	v_permlane32_swap_b32_e32 v113, v115
	s_and_saveexec_b64 s[60:61], s[8:9]
	v_pk_add_f32 v[112:113], v[112:113], v[114:115]
	ds_write_b64 v188, v[112:113] offset:4608
	s_or_b64 exec, exec, s[60:61]
	v_add_f32_e32 v112, v28, v29
	v_add_f32_e32 v113, v30, v31
	v_add_f32_e32 v112, v112, v113
	v_mul_f32_e32 v113, v29, v29
	v_mul_f32_e32 v114, v31, v31
	v_fmac_f32_e32 v113, v28, v28
	v_fmac_f32_e32 v114, v30, v30
	v_add_f32_e32 v113, v113, v114
	v_add_f32_e32 v114, v32, v33
	v_add_f32_e32 v115, v34, v35
	v_add_f32_e32 v112, 0, v112
	v_add_f32_e32 v114, v114, v115
	v_add_f32_e32 v112, v114, v112
	v_mul_f32_e32 v114, v33, v33
	v_mul_f32_e32 v115, v35, v35
	v_fmac_f32_e32 v114, v32, v32
	v_fmac_f32_e32 v115, v34, v34
	v_add_f32_e32 v114, v114, v115
	v_add_f32_e32 v113, v113, v114
	v_add_f32_e32 v114, v20, v21
	v_add_f32_e32 v115, v22, v23
	v_add_f32_e32 v114, v114, v115
	v_add_f32_e32 v112, v114, v112
	v_mul_f32_e32 v114, v21, v21
	v_mul_f32_e32 v115, v23, v23
	v_fmac_f32_e32 v114, v20, v20
	v_fmac_f32_e32 v115, v22, v22
	v_add_f32_e32 v114, v114, v115
	v_add_f32_e32 v113, v114, v113
	v_add_f32_e32 v114, v24, v25
	v_add_f32_e32 v115, v26, v27
	v_add_f32_e32 v114, v114, v115
	v_add_f32_e32 v112, v114, v112
	v_mul_f32_e32 v114, v25, v25
	v_mul_f32_e32 v115, v27, v27
	v_fmac_f32_e32 v114, v24, v24
	v_fmac_f32_e32 v115, v26, v26
	v_add_f32_e32 v114, v114, v115
	v_add_f32_e32 v113, v114, v113
	v_mov_b32_e32 v114, v112
	v_mov_b32_e32 v115, v113
	s_nop 0
	v_permlane16_swap_b32_e32 v112, v114
	v_permlane16_swap_b32_e32 v113, v115
	v_add_f32_e32 v112, v112, v114
	v_add_f32_e32 v113, v113, v115
	v_mov_b32_e32 v114, v112
	v_mov_b32_e32 v115, v113
	s_nop 0
	v_permlane32_swap_b32_e32 v112, v114
	v_permlane32_swap_b32_e32 v113, v115
	s_and_saveexec_b64 s[60:61], s[8:9]
	v_pk_add_f32 v[112:113], v[112:113], v[114:115]
	ds_write_b64 v188, v[112:113] offset:5120
	s_or_b64 exec, exec, s[60:61]
	v_add_f32_e32 v112, v12, v13
	v_add_f32_e32 v113, v14, v15
	v_add_f32_e32 v112, v112, v113
	v_mul_f32_e32 v113, v13, v13
	v_mul_f32_e32 v114, v15, v15
	v_fmac_f32_e32 v113, v12, v12
	v_fmac_f32_e32 v114, v14, v14
	v_add_f32_e32 v113, v113, v114
	v_add_f32_e32 v114, v16, v17
	v_add_f32_e32 v115, v18, v19
	v_add_f32_e32 v112, 0, v112
	v_add_f32_e32 v114, v114, v115
	v_add_f32_e32 v112, v114, v112
	v_mul_f32_e32 v114, v17, v17
	v_mul_f32_e32 v115, v19, v19
	v_fmac_f32_e32 v114, v16, v16
	v_fmac_f32_e32 v115, v18, v18
	v_add_f32_e32 v114, v114, v115
	v_add_f32_e32 v113, v113, v114
	v_add_f32_e32 v114, v4, v5
	v_add_f32_e32 v115, v6, v7
	v_add_f32_e32 v114, v114, v115
	v_add_f32_e32 v112, v114, v112
	v_mul_f32_e32 v114, v5, v5
	v_mul_f32_e32 v115, v7, v7
	v_fmac_f32_e32 v114, v4, v4
	v_fmac_f32_e32 v115, v6, v6
	v_add_f32_e32 v114, v114, v115
	v_add_f32_e32 v113, v114, v113
	v_add_f32_e32 v114, v8, v9
	v_add_f32_e32 v115, v10, v11
	v_add_f32_e32 v114, v114, v115
	v_add_f32_e32 v112, v114, v112
	v_mul_f32_e32 v114, v9, v9
	v_mul_f32_e32 v115, v11, v11
	v_fmac_f32_e32 v114, v8, v8
	v_fmac_f32_e32 v115, v10, v10
	v_add_f32_e32 v114, v114, v115
	v_add_f32_e32 v113, v114, v113
	v_mov_b32_e32 v114, v112
	v_mov_b32_e32 v115, v113
	s_nop 0
	v_permlane16_swap_b32_e32 v112, v114
	v_permlane16_swap_b32_e32 v113, v115
	v_add_f32_e32 v112, v112, v114
	v_add_f32_e32 v113, v113, v115
	v_mov_b32_e32 v114, v112
	v_mov_b32_e32 v115, v113
	s_nop 0
	v_permlane32_swap_b32_e32 v112, v114
	v_permlane32_swap_b32_e32 v113, v115
	s_and_saveexec_b64 s[60:61], s[8:9]
	v_pk_add_f32 v[112:113], v[112:113], v[114:115]
	ds_write_b64 v188, v[112:113] offset:5632
	s_or_b64 exec, exec, s[60:61]
	s_waitcnt lgkmcnt(0)
	s_barrier
	s_add_u32 s60, s22, 0x2ac00000
	v_add_u32_e32 v174, s82, v184
	s_addc_u32 s61, s23, 0
	v_ashrrev_i32_e32 v175, 31, v174
	s_and_saveexec_b64 vcc, s[10:11]
	s_cbranch_execz .LBB0_665
	ds_read_b128 v[112:115], v187
	ds_read_b128 v[120:123], v187 offset:16
	s_ashr_i32 s29, s28, 31
	s_waitcnt lgkmcnt(1)
	v_mov_b32_e32 v124, v112
	s_waitcnt lgkmcnt(0)
	v_mov_b32_e32 v125, v120
	v_mov_b32_e32 v126, v114
	v_mov_b32_e32 v127, v122
	v_pk_add_f32 v[124:125], v[124:125], v[126:127]
	v_mov_b32_e32 v120, v113
	v_mov_b32_e32 v122, v115
	v_add_f32_e32 v114, v124, v125
	v_pk_add_f32 v[112:113], v[120:121], v[122:123]
	s_nop 0
	v_add_f32_e32 v113, v112, v113
	v_mul_f32_e32 v112, 0x3b800000, v114
	v_fma_f32 v113, -v114, v112, v113
	v_lshlrev_b64 v[114:115], 6, v[174:175]
	v_lshl_add_u64 v[114:115], s[60:61], 0, v[114:115]
	v_max_f32_e32 v113, 0, v113
	v_lshl_add_u64 v[114:115], s[28:29], 3, v[114:115]
	global_store_dwordx2 v[114:115], v[112:113], off sc1

.LBB0_817:
	v_readlane_b32 s6, v254, 35
	s_waitcnt lgkmcnt(0)
	s_add_u32 s6, s26, s6
	s_addc_u32 s7, s27, 0
	s_add_u32 s45, s6, 0x100000
	s_addc_u32 s59, s7, 0
	s_lshr_b32 s6, s72, 14
	s_add_i32 s60, s6, 8
	s_ashr_i32 s61, s64, 4
	s_and_b64 s[6:7], s[18:19], exec
	s_cselect_b32 s6, s60, s61
	s_lshl_b32 s60, s82, 8
	s_mul_hi_i32 s7, s6, 0x4800
	s_mulk_i32 s6, 0x4800
	s_or_b32 s69, s60, s47
	s_lshl_b64 s[18:19], s[6:7], 2
	v_or_b32_e32 v132, s69, v181
	s_add_u32 s6, s45, s18
	s_addc_u32 s7, s59, s19
	v_ashrrev_i32_e32 v133, 31, v132
	v_lshl_add_u64 v[132:133], v[132:133], 2, s[6:7]
	s_mov_b32 s6, 0x10000
	v_add_co_u32_e32 v140, vcc, s6, v132
	v_lshl_add_u64 v[144:145], v[132:133], 0, s[76:77]
	s_nop 0
	v_addc_co_u32_e32 v141, vcc, 0, v133, vcc
	global_load_dwordx4 v[132:135], v[144:145], off offset:64
	global_load_dwordx4 v[136:139], v[144:145], off offset:512
	s_nop 0
	global_load_dwordx4 v[140:143], v[140:141], off
	s_nop 0
	global_load_dwordx4 v[152:155], v[144:145], off offset:576
	v_or3_b32 v144, v185, s47, v183
	v_add_u32_e32 v144, s60, v144
	v_ashrrev_i32_e32 v145, 31, v144
	v_readlane_b32 s6, v254, 46
	v_lshl_add_u64 v[178:179], v[144:145], 2, s[56:57]
	v_readlane_b32 s7, v254, 47
	v_lshl_add_u64 v[148:149], v[178:179], 0, s[36:37]
	global_load_dwordx4 v[144:147], v[148:149], off nt
	s_nop 0
	global_load_dwordx4 v[148:151], v[148:149], off offset:512 nt
	v_lshl_add_u64 v[166:167], v[178:179], 0, s[6:7]
	v_readlane_b32 s6, v254, 50
	global_load_dwordx4 v[156:159], v[166:167], off nt
	s_nop 0
	global_load_dwordx4 v[166:169], v[166:167], off offset:512 nt
	v_readlane_b32 s7, v254, 51
	v_lshl_add_u64 v[174:175], v[178:179], 0, s[42:43]
	global_load_dwordx4 v[170:173], v[174:175], off nt
	s_nop 0
	global_load_dwordx4 v[174:177], v[174:175], off offset:512 nt
	v_lshl_add_u64 v[196:197], v[178:179], 0, s[6:7]
	v_readlane_b32 s6, v254, 54
	v_readlane_b32 s7, v254, 55
	global_load_dwordx4 v[192:195], v[196:197], off nt
	s_nop 0
	global_load_dwordx4 v[196:199], v[196:197], off offset:512 nt
	v_lshl_add_u64 v[204:205], v[178:179], 0, s[48:49]
	v_lshl_add_u64 v[208:209], v[178:179], 0, s[6:7]
	v_readlane_b32 s6, v254, 58
	global_load_dwordx4 v[200:203], v[204:205], off nt
	s_nop 0
	global_load_dwordx4 v[204:207], v[204:205], off offset:512 nt
	s_nop 0
	global_load_dwordx4 v[214:217], v[208:209], off nt
	global_load_dwordx4 v[218:221], v[208:209], off offset:512 nt
	v_lshl_add_u64 v[208:209], v[178:179], 0, s[54:55]
	v_readlane_b32 s7, v254, 59
	global_load_dwordx4 v[222:225], v[208:209], off nt
	global_load_dwordx4 v[226:229], v[208:209], off offset:512 nt
	v_lshl_add_u64 v[208:209], v[178:179], 0, s[6:7]
	global_load_dwordx4 v[230:233], v[208:209], off nt
	global_load_dwordx4 v[234:237], v[208:209], off offset:512 nt
	s_waitcnt vmcnt(0)
	ds_write_b128 v184, v[144:147]
	ds_write_b128 v184, v[156:159] offset:1152
	ds_read_b128 v[144:147], v182
	ds_read_b128 v[238:241], v182 offset:64
	ds_write_b128 v184, v[148:151]
	ds_write_b128 v184, v[166:169] offset:1152
	ds_read_b128 v[148:151], v182
	ds_read_b128 v[250:253], v182 offset:64
	v_pk_add_f32 v[142:143], v[142:143], 1.0 op_sel_hi:[1,0]
	v_pk_add_f32 v[140:141], v[140:141], 1.0 op_sel_hi:[1,0]
	s_waitcnt lgkmcnt(5)
	v_pk_mul_f32 v[146:147], v[146:147], s[80:81] op_sel_hi:[1,0]
	v_pk_mul_f32 v[144:145], v[144:145], s[80:81] op_sel_hi:[1,0]
	v_pk_mul_f32 v[156:157], v[142:143], 0.5 op_sel_hi:[1,0]
	v_pk_mul_f32 v[158:159], v[140:141], 0.5 op_sel_hi:[1,0]
	ds_write_b128 v184, v[170:173]
	ds_write_b128 v184, v[192:195] offset:1152
	v_pk_fma_f32 v[142:143], v[130:131], v[156:157], v[146:147]
	v_pk_fma_f32 v[140:141], v[128:129], v[158:159], v[144:145]
	ds_read_b128 v[128:131], v182
	ds_read_b128 v[192:195], v182 offset:64
	v_pk_add_f32 v[134:135], v[134:135], 1.0 op_sel_hi:[1,0]
	v_pk_add_f32 v[132:133], v[132:133], 1.0 op_sel_hi:[1,0]
	s_waitcnt lgkmcnt(8)
	v_pk_mul_f32 v[144:145], v[240:241], s[80:81] op_sel_hi:[1,0]
	v_pk_mul_f32 v[208:209], v[238:239], s[80:81] op_sel_hi:[1,0]
	v_pk_mul_f32 v[166:167], v[134:135], 0.5 op_sel_hi:[1,0]
	v_pk_mul_f32 v[168:169], v[132:133], 0.5 op_sel_hi:[1,0]
	v_pk_fma_f32 v[146:147], v[126:127], v[166:167], v[144:145]
	v_pk_fma_f32 v[144:145], v[124:125], v[168:169], v[208:209]
	v_pk_add_f32 v[132:133], v[138:139], 1.0 op_sel_hi:[1,0]
	v_pk_add_f32 v[134:135], v[136:137], 1.0 op_sel_hi:[1,0]
	s_waitcnt lgkmcnt(5)
	v_pk_mul_f32 v[124:125], v[150:151], s[80:81] op_sel_hi:[1,0]
	v_pk_mul_f32 v[126:127], v[148:149], s[80:81] op_sel_hi:[1,0]
	v_pk_mul_f32 v[170:171], v[132:133], 0.5 op_sel_hi:[1,0]
	v_pk_mul_f32 v[172:173], v[134:135], 0.5 op_sel_hi:[1,0]
	ds_write_b128 v184, v[174:177]
	ds_write_b128 v184, v[196:199] offset:1152
	v_pk_fma_f32 v[150:151], v[122:123], v[170:171], v[124:125]
	v_pk_fma_f32 v[148:149], v[120:121], v[172:173], v[126:127]
	ds_read_b128 v[120:123], v182
	ds_read_b128 v[196:199], v182 offset:64
	v_pk_add_f32 v[132:133], v[154:155], 1.0 op_sel_hi:[1,0]
	v_pk_add_f32 v[134:135], v[152:153], 1.0 op_sel_hi:[1,0]
	s_waitcnt lgkmcnt(8)
	v_pk_mul_f32 v[124:125], v[252:253], s[80:81] op_sel_hi:[1,0]
	v_pk_mul_f32 v[126:127], v[250:251], s[80:81] op_sel_hi:[1,0]
	v_pk_mul_f32 v[174:175], v[132:133], 0.5 op_sel_hi:[1,0]
	v_pk_mul_f32 v[176:177], v[134:135], 0.5 op_sel_hi:[1,0]
	v_pk_fma_f32 v[154:155], v[110:111], v[174:175], v[124:125]
	v_pk_fma_f32 v[152:153], v[108:109], v[176:177], v[126:127]
	s_waitcnt lgkmcnt(5)
	v_pk_mul_f32 v[108:109], v[130:131], s[80:81] op_sel_hi:[1,0]
	v_pk_mul_f32 v[110:111], v[128:129], s[80:81] op_sel_hi:[1,0]
	v_pk_fma_f32 v[134:135], v[118:119], v[156:157], v[108:109]
	v_pk_fma_f32 v[132:133], v[116:117], v[158:159], v[110:111]
	s_waitcnt lgkmcnt(4)
	v_pk_mul_f32 v[108:109], v[194:195], s[80:81] op_sel_hi:[1,0]
	v_pk_mul_f32 v[110:111], v[192:193], s[80:81] op_sel_hi:[1,0]
	v_pk_fma_f32 v[138:139], v[114:115], v[166:167], v[108:109]
	v_pk_fma_f32 v[136:137], v[112:113], v[168:169], v[110:111]
	s_waitcnt lgkmcnt(1)
	v_pk_mul_f32 v[108:109], v[122:123], s[80:81] op_sel_hi:[1,0]
	v_pk_mul_f32 v[110:111], v[120:121], s[80:81] op_sel_hi:[1,0]
	v_pk_fma_f32 v[126:127], v[106:107], v[170:171], v[108:109]
	v_pk_fma_f32 v[124:125], v[104:105], v[172:173], v[110:111]
	s_waitcnt lgkmcnt(0)
	v_pk_mul_f32 v[104:105], v[198:199], s[80:81] op_sel_hi:[1,0]
	v_pk_mul_f32 v[106:107], v[196:197], s[80:81] op_sel_hi:[1,0]
	v_readlane_b32 s6, v254, 60
	v_pk_fma_f32 v[130:131], v[102:103], v[174:175], v[104:105]
	v_pk_fma_f32 v[128:129], v[100:101], v[176:177], v[106:107]
	v_readlane_b32 s7, v254, 61
	v_lshl_add_u64 v[104:105], v[178:179], 0, s[62:63]
	global_load_dwordx4 v[100:103], v[104:105], off nt
	s_nop 0
	global_load_dwordx4 v[104:107], v[104:105], off offset:512 nt
	v_lshl_add_u64 v[108:109], v[178:179], 0, s[6:7]
	v_readlane_b32 s6, v254, 62
	global_load_dwordx4 v[112:115], v[108:109], off nt
	global_load_dwordx4 v[192:195], v[108:109], off offset:512 nt
	v_lshl_add_u64 v[108:109], v[178:179], 0, s[96:97]
	v_readlane_b32 s7, v254, 63
	global_load_dwordx4 v[196:199], v[108:109], off nt
	global_load_dwordx4 v[238:241], v[108:109], off offset:512 nt
	v_lshl_add_u64 v[108:109], v[178:179], 0, s[6:7]
	global_load_dwordx4 v[250:253], v[108:109], off nt
	global_load_dwordx4 v[208:211], v[108:109], off offset:512 nt
	ds_write_b128 v184, v[200:203]
	ds_write_b128 v184, v[214:217] offset:1152
	ds_read_b128 v[108:111], v182
	ds_read_b128 v[120:123], v182 offset:64
	ds_write_b128 v184, v[204:207]
	ds_write_b128 v184, v[218:221] offset:1152
	ds_read_b128 v[200:203], v182
	ds_read_b128 v[204:207], v182 offset:64
	ds_write_b128 v184, v[222:225]
	ds_write_b128 v184, v[230:233] offset:1152
	ds_read_b128 v[214:217], v182
	ds_read_b128 v[218:221], v182 offset:64
	s_waitcnt lgkmcnt(9)
	v_pk_mul_f32 v[110:111], v[110:111], s[80:81] op_sel_hi:[1,0]
	v_pk_mul_f32 v[108:109], v[108:109], s[80:81] op_sel_hi:[1,0]
	v_pk_fma_f32 v[118:119], v[98:99], v[156:157], v[110:111]
	v_pk_fma_f32 v[116:117], v[96:97], v[158:159], v[108:109]
	s_waitcnt lgkmcnt(8)
	v_pk_mul_f32 v[96:97], v[122:123], s[80:81] op_sel_hi:[1,0]
	v_pk_mul_f32 v[98:99], v[120:121], s[80:81] op_sel_hi:[1,0]
	v_pk_fma_f32 v[122:123], v[94:95], v[166:167], v[96:97]
	v_pk_fma_f32 v[120:121], v[92:93], v[168:169], v[98:99]
	s_waitcnt lgkmcnt(5)
	v_pk_mul_f32 v[92:93], v[202:203], s[80:81] op_sel_hi:[1,0]
	v_pk_mul_f32 v[94:95], v[200:201], s[80:81] op_sel_hi:[1,0]
	ds_write_b128 v184, v[226:229]
	ds_write_b128 v184, v[234:237] offset:1152
	v_pk_fma_f32 v[98:99], v[90:91], v[170:171], v[92:93]
	v_pk_fma_f32 v[96:97], v[88:89], v[172:173], v[94:95]
	ds_read_b128 v[88:91], v182
	ds_read_b128 v[92:95], v182 offset:64
	s_waitcnt lgkmcnt(8)
	v_pk_mul_f32 v[108:109], v[206:207], s[80:81] op_sel_hi:[1,0]
	v_pk_mul_f32 v[200:201], v[204:205], s[80:81] op_sel_hi:[1,0]
	v_pk_fma_f32 v[110:111], v[74:75], v[174:175], v[108:109]
	v_pk_fma_f32 v[108:109], v[72:73], v[176:177], v[200:201]
	s_waitcnt lgkmcnt(5)
	v_pk_mul_f32 v[72:73], v[216:217], s[80:81] op_sel_hi:[1,0]
	v_pk_mul_f32 v[74:75], v[214:215], s[80:81] op_sel_hi:[1,0]
	v_pk_fma_f32 v[82:83], v[82:83], v[156:157], v[72:73]
	v_pk_fma_f32 v[80:81], v[80:81], v[158:159], v[74:75]
	s_waitcnt lgkmcnt(4)
	v_pk_mul_f32 v[72:73], v[220:221], s[80:81] op_sel_hi:[1,0]
	v_pk_mul_f32 v[74:75], v[218:219], s[80:81] op_sel_hi:[1,0]
	v_pk_fma_f32 v[86:87], v[86:87], v[166:167], v[72:73]
	v_pk_fma_f32 v[84:85], v[84:85], v[168:169], v[74:75]
	s_waitcnt lgkmcnt(1)
	v_pk_mul_f32 v[72:73], v[90:91], s[80:81] op_sel_hi:[1,0]
	v_pk_mul_f32 v[74:75], v[88:89], s[80:81] op_sel_hi:[1,0]
	v_pk_fma_f32 v[70:71], v[70:71], v[170:171], v[72:73]
	s_waitcnt lgkmcnt(0)
	v_pk_mul_f32 v[72:73], v[94:95], s[80:81] op_sel_hi:[1,0]
	v_pk_mul_f32 v[88:89], v[92:93], s[80:81] op_sel_hi:[1,0]
	v_pk_fma_f32 v[68:69], v[68:69], v[172:173], v[74:75]
	v_pk_fma_f32 v[74:75], v[66:67], v[174:175], v[72:73]
	v_pk_fma_f32 v[72:73], v[64:65], v[176:177], v[88:89]
	v_readlane_b32 s6, v255, 0
	v_lshl_add_u64 v[64:65], v[178:179], 0, s[70:71]
	v_readlane_b32 s7, v255, 1
	global_load_dwordx4 v[88:91], v[64:65], off nt
	global_load_dwordx4 v[92:95], v[64:65], off offset:512 nt
	v_lshl_add_u64 v[64:65], v[178:179], 0, s[6:7]
	v_readlane_b32 s6, v255, 2
	global_load_dwordx4 v[200:203], v[64:65], off nt
	global_load_dwordx4 v[204:207], v[64:65], off offset:512 nt
	v_lshl_add_u64 v[64:65], v[178:179], 0, s[14:15]
	v_readlane_b32 s7, v255, 3
	global_load_dwordx4 v[214:217], v[64:65], off nt
	global_load_dwordx4 v[218:221], v[64:65], off offset:512 nt
	v_lshl_add_u64 v[64:65], v[178:179], 0, s[6:7]
	global_load_dwordx4 v[222:225], v[64:65], off nt
	global_load_dwordx4 v[226:229], v[64:65], off offset:512 nt
	s_waitcnt vmcnt(15)
	ds_write_b128 v184, v[100:103]
	s_waitcnt vmcnt(13)
	ds_write_b128 v184, v[112:115] offset:1152
	ds_read_b128 v[64:67], v182
	ds_read_b128 v[100:103], v182 offset:64
	ds_write_b128 v184, v[104:107]
	s_waitcnt vmcnt(12)
	ds_write_b128 v184, v[192:195] offset:1152
	ds_read_b128 v[104:107], v182
	ds_read_b128 v[112:115], v182 offset:64
	s_waitcnt vmcnt(11)
	ds_write_b128 v184, v[196:199]
	s_waitcnt vmcnt(9)
	ds_write_b128 v184, v[250:253] offset:1152
	ds_read_b128 v[192:195], v182
	ds_read_b128 v[196:199], v182 offset:64
	s_waitcnt lgkmcnt(9)
	v_pk_mul_f32 v[64:65], v[64:65], s[80:81] op_sel_hi:[1,0]
	v_pk_mul_f32 v[66:67], v[66:67], s[80:81] op_sel_hi:[1,0]
	v_pk_fma_f32 v[60:61], v[60:61], v[158:159], v[64:65]
	s_waitcnt lgkmcnt(8)
	v_pk_mul_f32 v[64:65], v[102:103], s[80:81] op_sel_hi:[1,0]
	v_pk_mul_f32 v[100:101], v[100:101], s[80:81] op_sel_hi:[1,0]
	v_pk_fma_f32 v[62:63], v[62:63], v[156:157], v[66:67]
	v_pk_fma_f32 v[66:67], v[58:59], v[166:167], v[64:65]
	v_pk_fma_f32 v[64:65], v[56:57], v[168:169], v[100:101]
	ds_write_b128 v184, v[238:241]
	s_waitcnt vmcnt(8)
	ds_write_b128 v184, v[208:211] offset:1152
	s_waitcnt lgkmcnt(7)
	v_pk_mul_f32 v[56:57], v[106:107], s[80:81] op_sel_hi:[1,0]
	v_pk_mul_f32 v[58:59], v[104:105], s[80:81] op_sel_hi:[1,0]
	ds_read_b128 v[100:103], v182
	ds_read_b128 v[104:107], v182 offset:64
	v_pk_fma_f32 v[54:55], v[54:55], v[170:171], v[56:57]
	s_waitcnt lgkmcnt(8)
	v_pk_mul_f32 v[56:57], v[114:115], s[80:81] op_sel_hi:[1,0]
	v_pk_mul_f32 v[112:113], v[112:113], s[80:81] op_sel_hi:[1,0]
	v_pk_fma_f32 v[52:53], v[52:53], v[172:173], v[58:59]
	v_pk_fma_f32 v[58:59], v[42:43], v[174:175], v[56:57]
	v_pk_fma_f32 v[56:57], v[40:41], v[176:177], v[112:113]
	s_waitcnt lgkmcnt(5)
	v_pk_mul_f32 v[40:41], v[194:195], s[80:81] op_sel_hi:[1,0]
	v_pk_mul_f32 v[42:43], v[192:193], s[80:81] op_sel_hi:[1,0]
	v_pk_fma_f32 v[46:47], v[46:47], v[156:157], v[40:41]
	v_pk_fma_f32 v[44:45], v[44:45], v[158:159], v[42:43]
	s_waitcnt lgkmcnt(4)
	v_pk_mul_f32 v[40:41], v[198:199], s[80:81] op_sel_hi:[1,0]
	v_pk_mul_f32 v[42:43], v[196:197], s[80:81] op_sel_hi:[1,0]
	v_pk_fma_f32 v[50:51], v[50:51], v[166:167], v[40:41]
	v_pk_fma_f32 v[48:49], v[48:49], v[168:169], v[42:43]
	s_waitcnt lgkmcnt(1)
	v_pk_mul_f32 v[40:41], v[102:103], s[80:81] op_sel_hi:[1,0]
	v_pk_mul_f32 v[42:43], v[100:101], s[80:81] op_sel_hi:[1,0]
	v_pk_fma_f32 v[38:39], v[38:39], v[170:171], v[40:41]
	s_waitcnt lgkmcnt(0)
	v_pk_mul_f32 v[40:41], v[106:107], s[80:81] op_sel_hi:[1,0]
	v_pk_mul_f32 v[100:101], v[104:105], s[80:81] op_sel_hi:[1,0]
	v_pk_fma_f32 v[36:37], v[36:37], v[172:173], v[42:43]
	v_pk_fma_f32 v[42:43], v[34:35], v[174:175], v[40:41]
	v_pk_fma_f32 v[40:41], v[32:33], v[176:177], v[100:101]
	s_nop 0
	s_waitcnt vmcnt(7)
	ds_write_b128 v184, v[88:91]
	s_waitcnt vmcnt(5)
	ds_write_b128 v184, v[200:203] offset:1152
	ds_read_b128 v[32:35], v182
	ds_read_b128 v[88:91], v182 offset:64
	ds_write_b128 v184, v[92:95]
	s_waitcnt vmcnt(4)
	ds_write_b128 v184, v[204:207] offset:1152
	ds_read_b128 v[92:95], v182
	ds_read_b128 v[100:103], v182 offset:64
	s_waitcnt vmcnt(3)
	ds_write_b128 v184, v[214:217]
	s_waitcnt vmcnt(1)
	ds_write_b128 v184, v[222:225] offset:1152
	ds_read_b128 v[104:107], v182
	ds_read_b128 v[112:115], v182 offset:64
	s_waitcnt lgkmcnt(9)
	v_pk_mul_f32 v[32:33], v[32:33], s[80:81] op_sel_hi:[1,0]
	v_pk_mul_f32 v[34:35], v[34:35], s[80:81] op_sel_hi:[1,0]
	v_pk_fma_f32 v[28:29], v[28:29], v[158:159], v[32:33]
	s_waitcnt lgkmcnt(8)
	v_pk_mul_f32 v[32:33], v[90:91], s[80:81] op_sel_hi:[1,0]
	v_pk_mul_f32 v[88:89], v[88:89], s[80:81] op_sel_hi:[1,0]
	v_pk_fma_f32 v[30:31], v[30:31], v[156:157], v[34:35]
	v_pk_fma_f32 v[34:35], v[26:27], v[166:167], v[32:33]
	v_pk_fma_f32 v[32:33], v[24:25], v[168:169], v[88:89]
	ds_write_b128 v184, v[218:221]
	s_waitcnt vmcnt(0)
	ds_write_b128 v184, v[226:229] offset:1152
	s_waitcnt lgkmcnt(7)
	v_pk_mul_f32 v[24:25], v[94:95], s[80:81] op_sel_hi:[1,0]
	v_pk_mul_f32 v[26:27], v[92:93], s[80:81] op_sel_hi:[1,0]
	ds_read_b128 v[88:91], v182
	ds_read_b128 v[92:95], v182 offset:64
	v_pk_fma_f32 v[22:23], v[22:23], v[170:171], v[24:25]
	s_waitcnt lgkmcnt(8)
	v_pk_mul_f32 v[24:25], v[102:103], s[80:81] op_sel_hi:[1,0]
	v_pk_mul_f32 v[100:101], v[100:101], s[80:81] op_sel_hi:[1,0]
	v_pk_fma_f32 v[20:21], v[20:21], v[172:173], v[26:27]
	v_pk_fma_f32 v[26:27], v[14:15], v[174:175], v[24:25]
	v_pk_fma_f32 v[24:25], v[12:13], v[176:177], v[100:101]
	s_waitcnt lgkmcnt(5)
	v_pk_mul_f32 v[12:13], v[106:107], s[80:81] op_sel_hi:[1,0]
	v_pk_mul_f32 v[100:101], v[104:105], s[80:81] op_sel_hi:[1,0]
	v_pk_fma_f32 v[14:15], v[78:79], v[156:157], v[12:13]
	v_pk_fma_f32 v[12:13], v[76:77], v[158:159], v[100:101]
	s_waitcnt lgkmcnt(4)
	v_pk_mul_f32 v[76:77], v[114:115], s[80:81] op_sel_hi:[1,0]
	v_pk_mul_f32 v[78:79], v[112:113], s[80:81] op_sel_hi:[1,0]
	v_pk_fma_f32 v[18:19], v[18:19], v[166:167], v[76:77]
	v_pk_fma_f32 v[16:17], v[16:17], v[168:169], v[78:79]
	s_waitcnt lgkmcnt(1)
	v_pk_mul_f32 v[76:77], v[90:91], s[80:81] op_sel_hi:[1,0]
	v_pk_mul_f32 v[78:79], v[88:89], s[80:81] op_sel_hi:[1,0]
	v_pk_fma_f32 v[6:7], v[6:7], v[170:171], v[76:77]
	s_waitcnt lgkmcnt(0)
	v_pk_mul_f32 v[76:77], v[94:95], s[80:81] op_sel_hi:[1,0]
	v_pk_fma_f32 v[4:5], v[4:5], v[172:173], v[78:79]
	v_pk_mul_f32 v[78:79], v[92:93], s[80:81] op_sel_hi:[1,0]
	v_pk_fma_f32 v[10:11], v[10:11], v[174:175], v[76:77]
	v_add_f32_e32 v76, v140, v141
	v_add_f32_e32 v77, v142, v143
	v_pk_fma_f32 v[8:9], v[8:9], v[176:177], v[78:79]
	v_add_f32_e32 v76, v76, v77
	v_mul_f32_e32 v77, v141, v141
	v_mul_f32_e32 v78, v143, v143
	v_fmac_f32_e32 v77, v140, v140
	v_fmac_f32_e32 v78, v142, v142
	v_add_f32_e32 v77, v77, v78
	v_add_f32_e32 v78, v144, v145
	v_add_f32_e32 v79, v146, v147
	v_add_f32_e32 v76, 0, v76
	v_add_f32_e32 v78, v78, v79
	v_add_f32_e32 v76, v78, v76
	v_mul_f32_e32 v78, v145, v145
	v_mul_f32_e32 v79, v147, v147
	v_fmac_f32_e32 v78, v144, v144
	v_fmac_f32_e32 v79, v146, v146
	v_add_f32_e32 v78, v78, v79
	v_add_f32_e32 v77, v77, v78
	v_add_f32_e32 v78, v148, v149
	v_add_f32_e32 v79, v150, v151
	v_add_f32_e32 v78, v78, v79
	v_add_f32_e32 v76, v78, v76
	v_mul_f32_e32 v78, v149, v149
	v_mul_f32_e32 v79, v151, v151
	v_fmac_f32_e32 v78, v148, v148
	v_fmac_f32_e32 v79, v150, v150
	v_add_f32_e32 v78, v78, v79
	v_add_f32_e32 v77, v78, v77
	v_add_f32_e32 v78, v152, v153
	v_add_f32_e32 v79, v154, v155
	v_add_f32_e32 v78, v78, v79
	v_add_f32_e32 v76, v78, v76
	v_mul_f32_e32 v78, v153, v153
	v_mul_f32_e32 v79, v155, v155
	v_fmac_f32_e32 v78, v152, v152
	v_fmac_f32_e32 v79, v154, v154
	v_add_f32_e32 v78, v78, v79
	v_add_f32_e32 v77, v78, v77
	ds_swizzle_b32 v78, v76 offset:swizzle(SWAP,16)
	ds_swizzle_b32 v79, v77 offset:swizzle(SWAP,16)
	s_waitcnt lgkmcnt(1)
	v_add_f32_e32 v76, v76, v78
	s_waitcnt lgkmcnt(0)
	v_add_f32_e32 v77, v77, v79
	v_mov_b32_e32 v78, v76
	v_mov_b32_e32 v79, v77
	s_nop 0
	v_permlane32_swap_b32_e32 v76, v78
	v_permlane32_swap_b32_e32 v77, v79
	s_and_saveexec_b64 s[6:7], s[8:9]
	v_pk_add_f32 v[76:77], v[76:77], v[78:79]
	ds_write_b64 v190, v[76:77]
	s_or_b64 exec, exec, s[6:7]
	v_add_f32_e32 v76, v132, v133
	v_add_f32_e32 v77, v134, v135
	v_add_f32_e32 v76, v76, v77
	v_mul_f32_e32 v77, v133, v133
	v_mul_f32_e32 v78, v135, v135
	v_fmac_f32_e32 v77, v132, v132
	v_fmac_f32_e32 v78, v134, v134
	v_add_f32_e32 v77, v77, v78
	v_add_f32_e32 v78, v136, v137
	v_add_f32_e32 v79, v138, v139
	v_add_f32_e32 v76, 0, v76
	v_add_f32_e32 v78, v78, v79
	v_add_f32_e32 v76, v78, v76
	v_mul_f32_e32 v78, v137, v137
	v_mul_f32_e32 v79, v139, v139
	v_fmac_f32_e32 v78, v136, v136
	v_fmac_f32_e32 v79, v138, v138
	v_add_f32_e32 v78, v78, v79
	v_add_f32_e32 v77, v77, v78
	v_add_f32_e32 v78, v124, v125
	v_add_f32_e32 v79, v126, v127
	v_add_f32_e32 v78, v78, v79
	v_add_f32_e32 v76, v78, v76
	v_mul_f32_e32 v78, v125, v125
	v_mul_f32_e32 v79, v127, v127
	v_fmac_f32_e32 v78, v124, v124
	v_fmac_f32_e32 v79, v126, v126
	v_add_f32_e32 v78, v78, v79
	v_add_f32_e32 v77, v78, v77
	v_add_f32_e32 v78, v128, v129
	v_add_f32_e32 v79, v130, v131
	v_add_f32_e32 v78, v78, v79
	v_add_f32_e32 v76, v78, v76
	v_mul_f32_e32 v78, v129, v129
	v_mul_f32_e32 v79, v131, v131
	v_fmac_f32_e32 v78, v128, v128
	v_fmac_f32_e32 v79, v130, v130
	v_add_f32_e32 v78, v78, v79
	v_add_f32_e32 v77, v78, v77
	v_mov_b32_e32 v78, v76
	v_mov_b32_e32 v79, v77
	s_nop 0
	v_permlane16_swap_b32_e32 v76, v78
	v_permlane16_swap_b32_e32 v77, v79
	v_add_f32_e32 v76, v76, v78
	v_add_f32_e32 v77, v77, v79
	v_mov_b32_e32 v78, v76
	v_mov_b32_e32 v79, v77
	s_nop 0
	v_permlane32_swap_b32_e32 v76, v78
	v_permlane32_swap_b32_e32 v77, v79
	s_and_saveexec_b64 s[6:7], s[8:9]
	v_pk_add_f32 v[76:77], v[76:77], v[78:79]
	ds_write_b64 v190, v[76:77] offset:512
	s_or_b64 exec, exec, s[6:7]
	v_add_f32_e32 v76, v116, v117
	v_add_f32_e32 v77, v118, v119
	v_add_f32_e32 v76, v76, v77
	v_mul_f32_e32 v77, v117, v117
	v_mul_f32_e32 v78, v119, v119
	v_fmac_f32_e32 v77, v116, v116
	v_fmac_f32_e32 v78, v118, v118
	v_add_f32_e32 v77, v77, v78
	v_add_f32_e32 v78, v120, v121
	v_add_f32_e32 v79, v122, v123
	v_add_f32_e32 v76, 0, v76
	v_add_f32_e32 v78, v78, v79
	v_add_f32_e32 v76, v78, v76
	v_mul_f32_e32 v78, v121, v121
	v_mul_f32_e32 v79, v123, v123
	v_fmac_f32_e32 v78, v120, v120
	v_fmac_f32_e32 v79, v122, v122
	v_add_f32_e32 v78, v78, v79
	v_add_f32_e32 v77, v77, v78
	v_add_f32_e32 v78, v96, v97
	v_add_f32_e32 v79, v98, v99
	v_add_f32_e32 v78, v78, v79
	v_add_f32_e32 v76, v78, v76
	v_mul_f32_e32 v78, v97, v97
	v_mul_f32_e32 v79, v99, v99
	v_fmac_f32_e32 v78, v96, v96
	v_fmac_f32_e32 v79, v98, v98
	v_add_f32_e32 v78, v78, v79
	v_add_f32_e32 v77, v78, v77
	v_add_f32_e32 v78, v108, v109
	v_add_f32_e32 v79, v110, v111
	v_add_f32_e32 v78, v78, v79
	v_add_f32_e32 v76, v78, v76
	v_mul_f32_e32 v78, v109, v109
	v_mul_f32_e32 v79, v111, v111
	v_fmac_f32_e32 v78, v108, v108
	v_fmac_f32_e32 v79, v110, v110
	v_add_f32_e32 v78, v78, v79
	v_add_f32_e32 v77, v78, v77
	v_mov_b32_e32 v78, v76
	v_mov_b32_e32 v79, v77
	s_nop 0
	v_permlane16_swap_b32_e32 v76, v78
	v_permlane16_swap_b32_e32 v77, v79
	v_add_f32_e32 v76, v76, v78
	v_add_f32_e32 v77, v77, v79
	v_mov_b32_e32 v78, v76
	v_mov_b32_e32 v79, v77
	s_nop 0
	v_permlane32_swap_b32_e32 v76, v78
	v_permlane32_swap_b32_e32 v77, v79
	s_and_saveexec_b64 s[6:7], s[8:9]
	v_pk_add_f32 v[76:77], v[76:77], v[78:79]
	ds_write_b64 v190, v[76:77] offset:1024
	s_or_b64 exec, exec, s[6:7]
	v_add_f32_e32 v76, v80, v81
	v_add_f32_e32 v77, v82, v83
	v_add_f32_e32 v76, v76, v77
	v_mul_f32_e32 v77, v81, v81
	v_mul_f32_e32 v78, v83, v83
	v_fmac_f32_e32 v77, v80, v80
	v_fmac_f32_e32 v78, v82, v82
	v_add_f32_e32 v77, v77, v78
	v_add_f32_e32 v78, v84, v85
	v_add_f32_e32 v79, v86, v87
	v_add_f32_e32 v76, 0, v76
	v_add_f32_e32 v78, v78, v79
	v_add_f32_e32 v76, v78, v76
	v_mul_f32_e32 v78, v85, v85
	v_mul_f32_e32 v79, v87, v87
	v_fmac_f32_e32 v78, v84, v84
	v_fmac_f32_e32 v79, v86, v86
	v_add_f32_e32 v78, v78, v79
	v_add_f32_e32 v77, v77, v78
	v_add_f32_e32 v78, v68, v69
	v_add_f32_e32 v79, v70, v71
	v_add_f32_e32 v78, v78, v79
	v_add_f32_e32 v76, v78, v76
	v_mul_f32_e32 v78, v69, v69
	v_mul_f32_e32 v79, v71, v71
	v_fmac_f32_e32 v78, v68, v68
	v_fmac_f32_e32 v79, v70, v70
	v_add_f32_e32 v78, v78, v79
	v_add_f32_e32 v77, v78, v77
	v_add_f32_e32 v78, v72, v73
	v_add_f32_e32 v79, v74, v75
	v_add_f32_e32 v78, v78, v79
	v_add_f32_e32 v76, v78, v76
	v_mul_f32_e32 v78, v73, v73
	v_mul_f32_e32 v79, v75, v75
	v_fmac_f32_e32 v78, v72, v72
	v_fmac_f32_e32 v79, v74, v74
	v_add_f32_e32 v78, v78, v79
	v_add_f32_e32 v77, v78, v77
	v_mov_b32_e32 v78, v76
	v_mov_b32_e32 v79, v77
	s_nop 0
	v_permlane16_swap_b32_e32 v76, v78
	v_permlane16_swap_b32_e32 v77, v79
	v_add_f32_e32 v76, v76, v78
	v_add_f32_e32 v77, v77, v79
	v_mov_b32_e32 v78, v76
	v_mov_b32_e32 v79, v77
	s_nop 0
	v_permlane32_swap_b32_e32 v76, v78
	v_permlane32_swap_b32_e32 v77, v79
	s_and_saveexec_b64 s[6:7], s[8:9]
	v_pk_add_f32 v[76:77], v[76:77], v[78:79]
	ds_write_b64 v190, v[76:77] offset:1536
	s_or_b64 exec, exec, s[6:7]
	v_add_f32_e32 v76, v60, v61
	v_add_f32_e32 v77, v62, v63
	v_add_f32_e32 v76, v76, v77
	v_mul_f32_e32 v77, v61, v61
	v_mul_f32_e32 v78, v63, v63
	v_fmac_f32_e32 v77, v60, v60
	v_fmac_f32_e32 v78, v62, v62
	v_add_f32_e32 v77, v77, v78
	v_add_f32_e32 v78, v64, v65
	v_add_f32_e32 v79, v66, v67
	v_add_f32_e32 v76, 0, v76
	v_add_f32_e32 v78, v78, v79
	v_add_f32_e32 v76, v78, v76
	v_mul_f32_e32 v78, v65, v65
	v_mul_f32_e32 v79, v67, v67
	v_fmac_f32_e32 v78, v64, v64
	v_fmac_f32_e32 v79, v66, v66
	v_add_f32_e32 v78, v78, v79
	v_add_f32_e32 v77, v77, v78
	v_add_f32_e32 v78, v52, v53
	v_add_f32_e32 v79, v54, v55
	v_add_f32_e32 v78, v78, v79
	v_add_f32_e32 v76, v78, v76
	v_mul_f32_e32 v78, v53, v53
	v_mul_f32_e32 v79, v55, v55
	v_fmac_f32_e32 v78, v52, v52
	v_fmac_f32_e32 v79, v54, v54
	v_add_f32_e32 v78, v78, v79
	v_add_f32_e32 v77, v78, v77
	v_add_f32_e32 v78, v56, v57
	v_add_f32_e32 v79, v58, v59
	v_add_f32_e32 v78, v78, v79
	v_add_f32_e32 v76, v78, v76
	v_mul_f32_e32 v78, v57, v57
	v_mul_f32_e32 v79, v59, v59
	v_fmac_f32_e32 v78, v56, v56
	v_fmac_f32_e32 v79, v58, v58
	v_add_f32_e32 v78, v78, v79
	v_add_f32_e32 v77, v78, v77
	v_mov_b32_e32 v78, v76
	v_mov_b32_e32 v79, v77
	s_nop 0
	v_permlane16_swap_b32_e32 v76, v78
	v_permlane16_swap_b32_e32 v77, v79
	v_add_f32_e32 v76, v76, v78
	v_add_f32_e32 v77, v77, v79
	v_mov_b32_e32 v78, v76
	v_mov_b32_e32 v79, v77
	s_nop 0
	v_permlane32_swap_b32_e32 v76, v78
	v_permlane32_swap_b32_e32 v77, v79
	s_and_saveexec_b64 s[6:7], s[8:9]
	v_pk_add_f32 v[76:77], v[76:77], v[78:79]
	ds_write_b64 v190, v[76:77] offset:4096
	s_or_b64 exec, exec, s[6:7]
	v_add_f32_e32 v76, v44, v45
	v_add_f32_e32 v77, v46, v47
	v_add_f32_e32 v76, v76, v77
	v_mul_f32_e32 v77, v45, v45
	v_mul_f32_e32 v78, v47, v47
	v_fmac_f32_e32 v77, v44, v44
	v_fmac_f32_e32 v78, v46, v46
	v_add_f32_e32 v77, v77, v78
	v_add_f32_e32 v78, v48, v49
	v_add_f32_e32 v79, v50, v51
	v_add_f32_e32 v76, 0, v76
	v_add_f32_e32 v78, v78, v79
	v_add_f32_e32 v76, v78, v76
	v_mul_f32_e32 v78, v49, v49
	v_mul_f32_e32 v79, v51, v51
	v_fmac_f32_e32 v78, v48, v48
	v_fmac_f32_e32 v79, v50, v50
	v_add_f32_e32 v78, v78, v79
	v_add_f32_e32 v77, v77, v78
	v_add_f32_e32 v78, v36, v37
	v_add_f32_e32 v79, v38, v39
	v_add_f32_e32 v78, v78, v79
	v_add_f32_e32 v76, v78, v76
	v_mul_f32_e32 v78, v37, v37
	v_mul_f32_e32 v79, v39, v39
	v_fmac_f32_e32 v78, v36, v36
	v_fmac_f32_e32 v79, v38, v38
	v_add_f32_e32 v78, v78, v79
	v_add_f32_e32 v77, v78, v77
	v_add_f32_e32 v78, v40, v41
	v_add_f32_e32 v79, v42, v43
	v_add_f32_e32 v78, v78, v79
	v_add_f32_e32 v76, v78, v76
	v_mul_f32_e32 v78, v41, v41
	v_mul_f32_e32 v79, v43, v43
	v_fmac_f32_e32 v78, v40, v40
	v_fmac_f32_e32 v79, v42, v42
	v_add_f32_e32 v78, v78, v79
	v_add_f32_e32 v77, v78, v77
	v_mov_b32_e32 v78, v76
	v_mov_b32_e32 v79, v77
	s_nop 0
	v_permlane16_swap_b32_e32 v76, v78
	v_permlane16_swap_b32_e32 v77, v79
	v_add_f32_e32 v76, v76, v78
	v_add_f32_e32 v77, v77, v79
	v_mov_b32_e32 v78, v76
	v_mov_b32_e32 v79, v77
	s_nop 0
	v_permlane32_swap_b32_e32 v76, v78
	v_permlane32_swap_b32_e32 v77, v79
	s_and_saveexec_b64 s[6:7], s[8:9]
	v_pk_add_f32 v[76:77], v[76:77], v[78:79]
	ds_write_b64 v190, v[76:77] offset:4608
	s_or_b64 exec, exec, s[6:7]
	v_add_f32_e32 v76, v28, v29
	v_add_f32_e32 v77, v30, v31
	v_add_f32_e32 v76, v76, v77
	v_mul_f32_e32 v77, v29, v29
	v_mul_f32_e32 v78, v31, v31
	v_fmac_f32_e32 v77, v28, v28
	v_fmac_f32_e32 v78, v30, v30
	v_add_f32_e32 v77, v77, v78
	v_add_f32_e32 v78, v32, v33
	v_add_f32_e32 v79, v34, v35
	v_add_f32_e32 v76, 0, v76
	v_add_f32_e32 v78, v78, v79
	v_add_f32_e32 v76, v78, v76
	v_mul_f32_e32 v78, v33, v33
	v_mul_f32_e32 v79, v35, v35
	v_fmac_f32_e32 v78, v32, v32
	v_fmac_f32_e32 v79, v34, v34
	v_add_f32_e32 v78, v78, v79
	v_add_f32_e32 v77, v77, v78
	v_add_f32_e32 v78, v20, v21
	v_add_f32_e32 v79, v22, v23
	v_add_f32_e32 v78, v78, v79
	v_add_f32_e32 v76, v78, v76
	v_mul_f32_e32 v78, v21, v21
	v_mul_f32_e32 v79, v23, v23
	v_fmac_f32_e32 v78, v20, v20
	v_fmac_f32_e32 v79, v22, v22
	v_add_f32_e32 v78, v78, v79
	v_add_f32_e32 v77, v78, v77
	v_add_f32_e32 v78, v24, v25
	v_add_f32_e32 v79, v26, v27
	v_add_f32_e32 v78, v78, v79
	v_add_f32_e32 v76, v78, v76
	v_mul_f32_e32 v78, v25, v25
	v_mul_f32_e32 v79, v27, v27
	v_fmac_f32_e32 v78, v24, v24
	v_fmac_f32_e32 v79, v26, v26
	v_add_f32_e32 v78, v78, v79
	v_add_f32_e32 v77, v78, v77
	v_mov_b32_e32 v78, v76
	v_mov_b32_e32 v79, v77
	s_nop 0
	v_permlane16_swap_b32_e32 v76, v78
	v_permlane16_swap_b32_e32 v77, v79
	v_add_f32_e32 v76, v76, v78
	v_add_f32_e32 v77, v77, v79
	v_mov_b32_e32 v78, v76
	v_mov_b32_e32 v79, v77
	s_nop 0
	v_permlane32_swap_b32_e32 v76, v78
	v_permlane32_swap_b32_e32 v77, v79
	s_and_saveexec_b64 s[6:7], s[8:9]
	v_pk_add_f32 v[76:77], v[76:77], v[78:79]
	ds_write_b64 v190, v[76:77] offset:5120
	s_or_b64 exec, exec, s[6:7]
	v_add_f32_e32 v76, v12, v13
	v_add_f32_e32 v77, v14, v15
	v_add_f32_e32 v76, v76, v77
	v_mul_f32_e32 v77, v13, v13
	v_mul_f32_e32 v78, v15, v15
	v_fmac_f32_e32 v77, v12, v12
	v_fmac_f32_e32 v78, v14, v14
	v_add_f32_e32 v77, v77, v78
	v_add_f32_e32 v78, v16, v17
	v_add_f32_e32 v79, v18, v19
	v_add_f32_e32 v76, 0, v76
	v_add_f32_e32 v78, v78, v79
	v_add_f32_e32 v76, v78, v76
	v_mul_f32_e32 v78, v17, v17
	v_mul_f32_e32 v79, v19, v19
	v_fmac_f32_e32 v78, v16, v16
	v_fmac_f32_e32 v79, v18, v18
	v_add_f32_e32 v78, v78, v79
	v_add_f32_e32 v77, v77, v78
	v_add_f32_e32 v78, v4, v5
	v_add_f32_e32 v79, v6, v7
	v_add_f32_e32 v78, v78, v79
	v_add_f32_e32 v76, v78, v76
	v_mul_f32_e32 v78, v5, v5
	v_mul_f32_e32 v79, v7, v7
	v_fmac_f32_e32 v78, v4, v4
	v_fmac_f32_e32 v79, v6, v6
	v_add_f32_e32 v78, v78, v79
	v_add_f32_e32 v77, v78, v77
	v_add_f32_e32 v78, v8, v9
	v_add_f32_e32 v79, v10, v11
	v_add_f32_e32 v78, v78, v79
	v_add_f32_e32 v76, v78, v76
	v_mul_f32_e32 v78, v9, v9
	v_mul_f32_e32 v79, v11, v11
	v_fmac_f32_e32 v78, v8, v8
	v_fmac_f32_e32 v79, v10, v10
	v_add_f32_e32 v78, v78, v79
	v_add_f32_e32 v77, v78, v77
	v_mov_b32_e32 v78, v76
	v_mov_b32_e32 v79, v77
	s_nop 0
	v_permlane16_swap_b32_e32 v76, v78
	v_permlane16_swap_b32_e32 v77, v79
	v_add_f32_e32 v76, v76, v78
	v_add_f32_e32 v77, v77, v79
	v_mov_b32_e32 v78, v76
	v_mov_b32_e32 v79, v77
	s_nop 0
	v_permlane32_swap_b32_e32 v76, v78
	v_permlane32_swap_b32_e32 v77, v79
	s_and_saveexec_b64 s[6:7], s[8:9]
	v_pk_add_f32 v[76:77], v[76:77], v[78:79]
	ds_write_b64 v190, v[76:77] offset:5632
	s_or_b64 exec, exec, s[6:7]
	s_waitcnt lgkmcnt(0)
	s_barrier
	s_add_u32 s56, s26, 0x1ac00000
	v_add_u32_e32 v156, s68, v186
	s_addc_u32 s57, s27, 0
	v_ashrrev_i32_e32 v157, 31, v156
	s_and_saveexec_b64 s[6:7], s[10:11]
	s_cbranch_execz .LBB0_835
	ds_read_b128 v[76:79], v189
	ds_read_b128 v[88:91], v189 offset:16
	s_ashr_i32 s83, s82, 31
	s_waitcnt lgkmcnt(1)
	v_mov_b32_e32 v92, v76
	s_waitcnt lgkmcnt(0)
	v_mov_b32_e32 v93, v88
	v_mov_b32_e32 v94, v78
	v_mov_b32_e32 v95, v90
	v_pk_add_f32 v[92:93], v[92:93], v[94:95]
	v_mov_b32_e32 v88, v77
	v_mov_b32_e32 v90, v79
	v_add_f32_e32 v78, v92, v93
	v_pk_add_f32 v[76:77], v[88:89], v[90:91]
	s_nop 0
	v_add_f32_e32 v77, v76, v77
	v_mul_f32_e32 v76, 0x3b800000, v78
	v_fma_f32 v77, -v78, v76, v77
	v_lshlrev_b64 v[78:79], 6, v[156:157]
	v_lshl_add_u64 v[78:79], s[56:57], 0, v[78:79]
	v_max_f32_e32 v77, 0, v77
	v_lshl_add_u64 v[78:79], s[82:83], 3, v[78:79]
	global_store_dwordx2 v[78:79], v[76:77], off sc1
